# lru_pass: per-channel-block constants (softplus(lambda), b_a, b_x) cached in free LDS across items; all rw_scan edits (packed Tinv, hoists)
# speedup vs baseline: 1.0189x; 1.0120x over previous
; #define LAS __attribute__((address_space(3)))
; __device__ __forceinline__ bf16_t f2bf(float f) { return (bf16_t)(cvt_pk_bf16(f, 0.f) & 0xffffu); }
; __device__ __forceinline__ float bf2f(bf16_t b) { return __uint_as_float(((unsigned)b) << 16); }
; __device__ __forceinline__ void lru_pass(LAS unsigned char* L, int mode, const bf16_t* Z, const bf16_t* LWT, const float* conv_w, const float* conv_b, const float* b_a, const float* b_x, const float* lam,
;                          float* LSUM, const float* LCAR, bf16_t* Y) {
;     ...
;             const int d = tid & 63, ch = n * 64 + d; const float cw0 = conv_w[ch], cw1 = conv_w[512 + ch], cw2 = conv_w[1024 + ch], cw3 = conv_w[1536 + ch], cbv = conv_b[ch];
; #pragma unroll
;             for (int k8 = 0; k8 < 8; ++k8) { const int i = (tid >> 6) + 8 * k8;
;                 const float acc = cbv + bf2f(XS[i * 72 + d]) * cw0 + bf2f(XS[(i + 1) * 72 + d]) * cw1 + bf2f(XS[(i + 2) * 72 + d]) * cw2 + bf2f(XS[(i + 3) * 72 + d]) * cw3;
;                 xc[i * 65 + d] = acc; xcb[i * 72 + d] = f2bf(acc); } }
;         if (n != nprev) { nprev = n;
;         for (int idx = tid; idx < 2048; idx += 512) { const int mat = idx >> 9, d = (idx >> 3) & 63, sg = idx & 7, kind = mat >> 1, g = mat & 1;
;             *(LAS bf16x8*)(LW + mat * 64 * 72 + d * 72 + sg * 8) = *(const bf16x8*)(LWT + (size_t)(kind * 16 + g * 8 + n) * 4096 + d * 64 + sg * 8); } }
.LBB0_599:
	s_or_b64 exec, exec, s[20:21]
	v_or_b32_e32 v48, v46, v41
	v_mov_b32_e32 v49, v0
	v_lshlrev_b64 v[2:3], 2, v[48:49]
	v_lshl_add_u64 v[4:5], s[46:47], 0, v[2:3]
	s_waitcnt lgkmcnt(0)
	s_barrier
	global_load_dword v6, v[4:5], off
	global_load_dword v7, v[4:5], off offset:2048
	v_add_co_u32_e32 v4, vcc, 0x1000, v4
	v_lshl_add_u64 v[2:3], s[48:49], 0, v[2:3]
	s_nop 0
	v_addc_co_u32_e32 v5, vcc, 0, v5, vcc
	global_load_dword v8, v[4:5], off
	s_nop 0
	global_load_dword v4, v[4:5], off offset:2048
	ds_read_u16 v5, v58 offset:144
	global_load_dword v2, v[2:3], off
	ds_read_u16 v3, v57
	s_cmp_lg_u32 s39, s4
	s_cselect_b64 s[20:21], -1, 0
	s_cselect_b32 s98, 0, 1
	s_waitcnt lgkmcnt(1)
	v_lshlrev_b32_e32 v5, 16, v5
	s_and_b64 s[4:5], s[64:65], s[20:21]
	s_waitcnt lgkmcnt(0)
	v_lshlrev_b32_e32 v3, 16, v3
	s_waitcnt vmcnt(0)
	v_fma_f32 v3, v6, v3, v2
	v_fmac_f32_e32 v3, v7, v5
	ds_read_u16 v5, v58 offset:288
	s_waitcnt lgkmcnt(0)
	v_lshlrev_b32_e32 v5, 16, v5
	v_fmac_f32_e32 v3, v8, v5
	ds_read_u16 v5, v58 offset:432
	s_waitcnt lgkmcnt(0)
	v_lshlrev_b32_e32 v5, 16, v5
	v_fmac_f32_e32 v3, v4, v5
	ds_write_b32 v245, v3
	v_cvt_pk_bf16_f32 v3, v3, s0
	ds_write_b16 v59, v3 offset:16640
	v_add_u32_e32 v3, 0x480, v57
	ds_read_u16 v3, v3
	ds_read_u16 v5, v60 offset:144
	s_waitcnt lgkmcnt(1)
	v_lshlrev_b32_e32 v3, 16, v3
	v_fma_f32 v3, v6, v3, v2
	s_waitcnt lgkmcnt(0)
	v_lshlrev_b32_e32 v5, 16, v5
	v_fmac_f32_e32 v3, v7, v5
	ds_read_u16 v5, v60 offset:288
	s_waitcnt lgkmcnt(0)
	v_lshlrev_b32_e32 v5, 16, v5
	v_fmac_f32_e32 v3, v8, v5
	ds_read_u16 v5, v60 offset:432
	s_waitcnt lgkmcnt(0)
	v_lshlrev_b32_e32 v5, 16, v5
	v_fmac_f32_e32 v3, v4, v5
	ds_write_b32 v245, v3 offset:2080
	v_cvt_pk_bf16_f32 v3, v3, s0
	ds_write_b16 v59, v3 offset:17792
	v_add_u32_e32 v3, 0x900, v57
	ds_read_u16 v3, v3
	ds_read_u16 v5, v61 offset:144
	s_waitcnt lgkmcnt(1)
	v_lshlrev_b32_e32 v3, 16, v3
	v_fma_f32 v3, v6, v3, v2
	s_waitcnt lgkmcnt(0)
	v_lshlrev_b32_e32 v5, 16, v5
	v_fmac_f32_e32 v3, v7, v5
	ds_read_u16 v5, v61 offset:288
	s_waitcnt lgkmcnt(0)
	v_lshlrev_b32_e32 v5, 16, v5
	v_fmac_f32_e32 v3, v8, v5
	ds_read_u16 v5, v61 offset:432
	s_waitcnt lgkmcnt(0)
	v_lshlrev_b32_e32 v5, 16, v5
	v_fmac_f32_e32 v3, v4, v5
	ds_write_b32 v245, v3 offset:4160
	v_cvt_pk_bf16_f32 v3, v3, s0
	ds_write_b16 v59, v3 offset:18944
	v_add_u32_e32 v3, 0xd80, v57
	ds_read_u16 v3, v3
	ds_read_u16 v5, v62 offset:144
	s_waitcnt lgkmcnt(1)
	v_lshlrev_b32_e32 v3, 16, v3
	v_fma_f32 v3, v6, v3, v2
	s_waitcnt lgkmcnt(0)
	v_lshlrev_b32_e32 v5, 16, v5
	v_fmac_f32_e32 v3, v7, v5
	ds_read_u16 v5, v62 offset:288
	s_waitcnt lgkmcnt(0)
	v_lshlrev_b32_e32 v5, 16, v5
	v_fmac_f32_e32 v3, v8, v5
	ds_read_u16 v5, v62 offset:432
	s_waitcnt lgkmcnt(0)
	v_lshlrev_b32_e32 v5, 16, v5
	v_fmac_f32_e32 v3, v4, v5
	ds_write_b32 v245, v3 offset:6240
	v_cvt_pk_bf16_f32 v3, v3, s0
	ds_write_b16 v59, v3 offset:20096
	v_add_u32_e32 v3, 0x1200, v57
	ds_read_u16 v3, v3
	ds_read_u16 v5, v63 offset:144
	s_waitcnt lgkmcnt(1)
	v_lshlrev_b32_e32 v3, 16, v3
	v_fma_f32 v3, v6, v3, v2
	s_waitcnt lgkmcnt(0)
	v_lshlrev_b32_e32 v5, 16, v5
	v_fmac_f32_e32 v3, v7, v5
	ds_read_u16 v5, v63 offset:288
	s_waitcnt lgkmcnt(0)
	v_lshlrev_b32_e32 v5, 16, v5
	v_fmac_f32_e32 v3, v8, v5
	ds_read_u16 v5, v63 offset:432
	s_waitcnt lgkmcnt(0)
	v_lshlrev_b32_e32 v5, 16, v5
	v_fmac_f32_e32 v3, v4, v5
	ds_write_b32 v245, v3 offset:8320
	v_cvt_pk_bf16_f32 v3, v3, s0
	ds_write_b16 v59, v3 offset:21248
	v_add_u32_e32 v3, 0x1680, v57
	ds_read_u16 v3, v3
	ds_read_u16 v5, v64 offset:144
	s_waitcnt lgkmcnt(1)
	v_lshlrev_b32_e32 v3, 16, v3
	v_fma_f32 v3, v6, v3, v2
	s_waitcnt lgkmcnt(0)
	v_lshlrev_b32_e32 v5, 16, v5
	v_fmac_f32_e32 v3, v7, v5
	ds_read_u16 v5, v64 offset:288
	s_waitcnt lgkmcnt(0)
	v_lshlrev_b32_e32 v5, 16, v5
	v_fmac_f32_e32 v3, v8, v5
	ds_read_u16 v5, v64 offset:432
	s_waitcnt lgkmcnt(0)
	v_lshlrev_b32_e32 v5, 16, v5
	v_fmac_f32_e32 v3, v4, v5
	ds_write_b32 v245, v3 offset:10400
	v_cvt_pk_bf16_f32 v3, v3, s0
	ds_write_b16 v59, v3 offset:22400
	v_add_u32_e32 v3, 0x1b00, v57
	ds_read_u16 v3, v3
	ds_read_u16 v5, v65 offset:144
	s_waitcnt lgkmcnt(1)
	v_lshlrev_b32_e32 v3, 16, v3
	v_fma_f32 v3, v6, v3, v2
	s_waitcnt lgkmcnt(0)
	v_lshlrev_b32_e32 v5, 16, v5
	v_fmac_f32_e32 v3, v7, v5
	ds_read_u16 v5, v65 offset:288
	s_waitcnt lgkmcnt(0)
	v_lshlrev_b32_e32 v5, 16, v5
	v_fmac_f32_e32 v3, v8, v5
	ds_read_u16 v5, v65 offset:432
	s_waitcnt lgkmcnt(0)
	v_lshlrev_b32_e32 v5, 16, v5
	v_fmac_f32_e32 v3, v4, v5
	ds_write_b32 v245, v3 offset:12480
	v_cvt_pk_bf16_f32 v3, v3, s0
	ds_write_b16 v59, v3 offset:23552
	v_add_u32_e32 v3, 0x1f80, v57
	ds_read_u16 v3, v3
	s_waitcnt lgkmcnt(0)
	v_lshlrev_b32_e32 v3, 16, v3
	v_fmac_f32_e32 v2, v6, v3
	ds_read_u16 v3, v248 offset:144
	s_waitcnt lgkmcnt(0)
	v_lshlrev_b32_e32 v3, 16, v3
	v_fmac_f32_e32 v2, v7, v3
	ds_read_u16 v3, v248 offset:288
	s_waitcnt lgkmcnt(0)
	v_lshlrev_b32_e32 v3, 16, v3
	v_fmac_f32_e32 v2, v8, v3
	ds_read_u16 v3, v248 offset:432
	s_waitcnt lgkmcnt(0)
	v_lshlrev_b32_e32 v3, 16, v3
	v_fmac_f32_e32 v2, v4, v3
	ds_write_b32 v245, v2 offset:14560
	v_cvt_pk_bf16_f32 v2, v2, s0
	ds_write_b16 v59, v2 offset:24704
	s_and_saveexec_b64 s[20:21], s[4:5]
	s_cbranch_execz .LBB0_602
	s_mov_b64 s[22:23], 0
	v_mov_b32_e32 v2, v94
	v_mov_b32_e32 v3, v1

; __device__ __forceinline__ f32x4 mma16(bf16x8 a, bf16x8 b, f32x4 c) { return __builtin_amdgcn_mfma_f32_16x16x32_bf16(a, b, c, 0, 0, 0); }
; __device__ __forceinline__ void lru_pass(LAS unsigned char* L, int mode, const bf16_t* Z, const bf16_t* LWT, const float* conv_w, const float* conv_b, const float* b_a, const float* b_x, const float* lam,
;                          float* LSUM, const float* LCAR, bf16_t* Y) {
;     ...
;         __syncthreads();
;         { const int g = wid >> 2, ti = wid & 3; f32x4 aa[4], ax[4];
; #pragma unroll
;             for (int td = 0; td < 4; ++td) { aa[td] = (f32x4){0.f, 0.f, 0.f, 0.f}; ax[td] = (f32x4){0.f, 0.f, 0.f, 0.f}; }
; #pragma unroll
;             for (int kk = 0; kk < 2; ++kk) { const bf16x8 av = lfrag(xcb, 72, ti * 16 + fr, kk * 32 + 8 * fq);
; #pragma unroll
;                 for (int td = 0; td < 4; ++td) { aa[td] = mma16(av, lfrag(LW + g * 64 * 72, 72, td * 16 + fr, kk * 32 + 8 * fq), aa[td]);
;                     ax[td] = mma16(av, lfrag(LW + (2 + g) * 64 * 72, 72, td * 16 + fr, kk * 32 + 8 * fq), ax[td]); } }
; #pragma unroll
;             for (int td = 0; td < 4; ++td) { const int d = td * 16 + fr, ch = n * 64 + d; const float lm = lam[g * 512 + ch]; const float sp = lm > 0.f ? log1pf(expf(-lm)) : -lm + log1pf(expf(lm));
.LBB0_602:
	s_or_b64 exec, exec, s[20:21]
	s_waitcnt lgkmcnt(0)
	s_barrier
	ds_read_b128 v[2:5], v66 offset:16640
	ds_read_b128 v[6:9], v67 offset:25856
	ds_read_b128 v[22:25], v67 offset:30464
	ds_read_b128 v[18:21], v67 offset:46592
	s_waitcnt lgkmcnt(1)
	v_mfma_f32_16x16x32_bf16 v[50:53], v[2:5], v[22:25], 0
	ds_read_b128 v[22:25], v67 offset:48896
	ds_read_b128 v[10:13], v67 offset:44288
	ds_read_b128 v[14:17], v67 offset:28160
	s_waitcnt lgkmcnt(2)
	v_mfma_f32_16x16x32_bf16 v[206:209], v[2:5], v[22:25], 0
	ds_read_b128 v[22:25], v67 offset:32768
	s_waitcnt lgkmcnt(0)
	v_mfma_f32_16x16x32_bf16 v[210:213], v[2:5], v[22:25], 0
	ds_read_b128 v[22:25], v67 offset:51200
	v_mfma_f32_16x16x32_bf16 v[6:9], v[2:5], v[6:9], 0
	v_mfma_f32_16x16x32_bf16 v[10:13], v[2:5], v[10:13], 0
	v_mfma_f32_16x16x32_bf16 v[14:17], v[2:5], v[14:17], 0
	v_mfma_f32_16x16x32_bf16 v[18:21], v[2:5], v[18:21], 0
	s_waitcnt lgkmcnt(0)
	v_mfma_f32_16x16x32_bf16 v[2:5], v[2:5], v[22:25], 0
	ds_read_b128 v[214:217], v66 offset:16704
	ds_read_b128 v[22:25], v67 offset:25920
	s_waitcnt lgkmcnt(0)
	v_mfma_f32_16x16x32_bf16 v[30:33], v[214:217], v[22:25], v[6:9]
	s_nop 2
	ds_read_b128 v[6:9], v67 offset:44352
	s_waitcnt lgkmcnt(0)
	v_mfma_f32_16x16x32_bf16 v[26:29], v[214:217], v[6:9], v[10:13]
	ds_read_b128 v[6:9], v67 offset:28224
	s_waitcnt lgkmcnt(0)
	v_mfma_f32_16x16x32_bf16 v[22:25], v[214:217], v[6:9], v[14:17]
	ds_read_b128 v[6:9], v67 offset:46656
	s_waitcnt lgkmcnt(0)
	v_mfma_f32_16x16x32_bf16 v[18:21], v[214:217], v[6:9], v[18:21]
	ds_read_b128 v[6:9], v67 offset:30528
	s_waitcnt lgkmcnt(0)
	v_mfma_f32_16x16x32_bf16 v[14:17], v[214:217], v[6:9], v[50:53]
	ds_read_b128 v[6:9], v67 offset:48960
	s_nop 1
	ds_read_b128 v[50:53], v67 offset:51264
	s_waitcnt lgkmcnt(1)
	v_mfma_f32_16x16x32_bf16 v[10:13], v[214:217], v[6:9], v[206:209]
	ds_read_b128 v[6:9], v67 offset:32832
	s_waitcnt lgkmcnt(1)
	v_mfma_f32_16x16x32_bf16 v[2:5], v[214:217], v[50:53], v[2:5]
	v_add_u32_e32 v50, v46, v55
	v_or_b32_e32 v52, v50, v34
	v_ashrrev_i32_e32 v53, 31, v52
	v_lshl_add_u64 v[206:207], v[52:53], 2, s[54:55]
	s_cmp_lg_u32 s98, 0
	s_cbranch_scc1 .Llru_c0_a
	global_load_dword v45, v[206:207], off
; __device__ __forceinline__ void lru_pass(LAS unsigned char* L, int mode, const bf16_t* Z, const bf16_t* LWT, const float* conv_w, const float* conv_b, const float* b_a, const float* b_x, const float* lam,
;                          float* LSUM, const float* LCAR, bf16_t* Y) {
;     ...
;             for (int td = 0; td < 4; ++td) { const int d = td * 16 + fr, ch = n * 64 + d; const float lm = lam[g * 512 + ch]; const float sp = lm > 0.f ? log1pf(expf(-lm)) : -lm + log1pf(expf(lm));
.Llru_c0_a:
	s_waitcnt lgkmcnt(0)
	v_mfma_f32_16x16x32_bf16 v[6:9], v[214:217], v[6:9], v[210:213]
	s_cmp_lg_u32 s98, 0
	s_cbranch_scc1 .Llru_c0_b
	s_waitcnt vmcnt(0)
	v_cmp_nlt_f32_e32 vcc, 0, v45
	s_and_saveexec_b64 s[4:5], vcc
	s_xor_b64 s[20:21], exec, s[4:5]
	s_cbranch_execz .LBB0_604
	v_mul_f32_e32 v36, 0x3fb8aa3b, v45
	v_rndne_f32_e32 v37, v36
	v_sub_f32_e32 v38, v36, v37
	v_fma_f32 v36, v45, s15, -v36
	v_fmac_f32_e32 v36, 0x32a5705f, v45
	v_add_f32_e32 v36, v38, v36
	v_cvt_i32_f32_e32 v37, v37
	v_exp_f32_e32 v36, v36
	s_mov_b32 s3, 0xc2ce8ed0
	v_cmp_ngt_f32_e32 vcc, s3, v45
	s_mov_b32 s3, 0x42b17218
	v_ldexp_f32 v36, v36, v37
	v_cndmask_b32_e32 v36, 0, v36, vcc
	v_cmp_nlt_f32_e32 vcc, s3, v45
	s_mov_b32 s3, 0x33800000
	s_nop 0
	v_cndmask_b32_e32 v36, v222, v36, vcc
	v_add_f32_e32 v37, 1.0, v36
	v_add_f32_e32 v38, -1.0, v37
	v_sub_f32_e32 v39, v38, v37
	v_add_f32_e32 v39, 1.0, v39
	v_sub_f32_e32 v38, v36, v38
	v_add_f32_e32 v38, v38, v39
	v_frexp_mant_f32_e32 v39, v37
	v_cvt_f64_f32_e32 v[206:207], v37
	v_frexp_exp_i32_f64_e32 v42, v[206:207]
	v_cmp_gt_f32_e32 vcc, s11, v39
	s_nop 1
	v_subbrev_co_u32_e32 v39, vcc, 0, v42, vcc
	v_sub_u32_e32 v42, 0, v39
	v_ldexp_f32 v37, v37, v42
	v_ldexp_f32 v38, v38, v42
	v_add_f32_e32 v42, -1.0, v37
	v_add_f32_e32 v47, 1.0, v37
	v_add_f32_e32 v43, 1.0, v42
	v_add_f32_e32 v51, -1.0, v47
	v_sub_f32_e32 v43, v37, v43
	v_sub_f32_e32 v37, v37, v51
	v_add_f32_e32 v37, v38, v37
	v_add_f32_e32 v43, v38, v43
	v_add_f32_e32 v38, v47, v37
	v_sub_f32_e32 v47, v47, v38
	v_add_f32_e32 v37, v37, v47
	v_rcp_f32_e32 v47, v38
	v_add_f32_e32 v207, v42, v43
	v_sub_f32_e32 v42, v42, v207
	v_add_f32_e32 v42, v43, v42
	v_mul_f32_e32 v43, v207, v47
	v_mul_f32_e32 v208, v38, v43
	v_fma_f32 v210, v43, v38, -v208
	v_fmac_f32_e32 v210, v43, v37
	v_add_f32_e32 v206, v208, v210
	v_sub_f32_e32 v209, v207, v206
	v_pk_add_f32 v[212:213], v[206:207], v[208:209] neg_lo:[0,1] neg_hi:[0,1]
	v_mov_b32_e32 v211, v206
	v_pk_add_f32 v[206:207], v[212:213], v[210:211] neg_lo:[0,1] neg_hi:[0,1]
	v_cmp_neq_f32_e32 vcc, s2, v36
	v_add_f32_e32 v42, v42, v207
	v_add_f32_e32 v42, v206, v42
	v_add_f32_e32 v207, v209, v42
	v_mul_f32_e32 v51, v47, v207
	v_mul_f32_e32 v208, v38, v51
	v_fma_f32 v210, v51, v38, -v208
	v_fmac_f32_e32 v210, v51, v37
	v_add_f32_e32 v206, v208, v210
	v_sub_f32_e32 v37, v209, v207
	v_sub_f32_e32 v209, v207, v206
	v_pk_add_f32 v[212:213], v[206:207], v[208:209] neg_lo:[0,1] neg_hi:[0,1]
	v_mov_b32_e32 v211, v206
	v_add_f32_e32 v37, v42, v37
	v_pk_add_f32 v[206:207], v[212:213], v[210:211] neg_lo:[0,1] neg_hi:[0,1]
	v_add_f32_e32 v38, v43, v51
	v_add_f32_e32 v37, v37, v207
	v_add_f32_e32 v37, v206, v37
	v_add_f32_e32 v37, v209, v37
	v_sub_f32_e32 v42, v38, v43
	v_mul_f32_e32 v37, v47, v37
	v_sub_f32_e32 v42, v51, v42
	v_add_f32_e32 v37, v42, v37
	v_add_f32_e32 v42, v38, v37
	v_cvt_f32_i32_e32 v206, v39
	v_mul_f32_e32 v43, v42, v42
	v_fmamk_f32 v47, v43, 0x3e9b6dac, v220
	v_fmaak_f32 v155, v43, v47, 0x3f2aaada
	v_mul_f32_e32 v207, v42, v43
	v_pk_mul_f32 v[210:211], v[206:207], v[154:155]
	v_ldexp_f32 v209, v42, 1
	v_fma_f32 v208, v206, s14, -v210
	v_fmac_f32_e32 v208, 0xb102e308, v206
	v_sub_f32_e32 v38, v42, v38
	v_pk_add_f32 v[206:207], v[210:211], v[208:209]
	v_sub_f32_e32 v37, v37, v38
	v_sub_f32_e32 v38, v207, v209
	v_ldexp_f32 v37, v37, 1
	v_sub_f32_e32 v38, v211, v38
	v_add_f32_e32 v213, v37, v38
	v_mov_b32_e32 v212, v210
	v_pk_add_f32 v[210:211], v[206:207], v[210:211] neg_lo:[0,1] neg_hi:[0,1]
	v_pk_add_f32 v[214:215], v[206:207], v[212:213]
	v_mov_b32_e32 v209, v206
	v_mov_b32_e32 v211, v215
	v_pk_add_f32 v[216:217], v[208:209], v[210:211] neg_lo:[0,1] neg_hi:[0,1]
	v_pk_add_f32 v[208:209], v[208:209], v[210:211]
	v_mov_b32_e32 v212, v213
	v_pk_add_f32 v[210:211], v[208:209], v[206:207] op_sel:[1,0] op_sel_hi:[0,1] neg_lo:[0,1] neg_hi:[0,1]
	v_pk_add_f32 v[218:219], v[214:215], v[210:211] op_sel_hi:[1,0] neg_lo:[0,1] neg_hi:[0,1]
	v_mov_b32_e32 v214, v215
	v_mov_b32_e32 v215, v209
	v_pk_mov_b32 v[210:211], v[206:207], v[210:211] op_sel:[1,0]
	v_mov_b32_e32 v213, v206
	v_pk_add_f32 v[210:211], v[214:215], v[210:211] neg_lo:[0,1] neg_hi:[0,1]
	v_mov_b32_e32 v218, v216
	v_pk_add_f32 v[206:207], v[212:213], v[210:211] neg_lo:[0,1] neg_hi:[0,1]
	v_mov_b32_e32 v217, v209
	v_pk_add_f32 v[210:211], v[218:219], v[206:207]
	s_nop 0
	v_pk_add_f32 v[212:213], v[210:211], v[210:211] op_sel:[0,1] op_sel_hi:[1,0]
	s_nop 0
	v_pk_add_f32 v[208:209], v[208:209], v[212:213] op_sel:[1,0] op_sel_hi:[0,1]
	v_mov_b32_e32 v211, v208
	v_pk_add_f32 v[214:215], v[210:211], v[216:217] neg_lo:[0,1] neg_hi:[0,1]
	v_mov_b32_e32 v207, v212
	v_sub_f32_e32 v37, v210, v214
	v_pk_add_f32 v[206:207], v[206:207], v[214:215] neg_lo:[0,1] neg_hi:[0,1]
	v_sub_f32_e32 v37, v216, v37
	v_add_f32_e32 v37, v206, v37
	v_add_f32_e32 v37, v37, v207
	v_add_f32_e32 v37, v208, v37
	v_cndmask_b32_e32 v37, v222, v37, vcc
	v_cmp_lt_f32_e64 vcc, |v36|, s3
	s_nop 1
	v_cndmask_b32_e32 v36, v37, v36, vcc
	v_sub_f32_e32 v54, v36, v45

; __device__ __forceinline__ float sigm(float x) { return __builtin_amdgcn_rcpf(1.f + __expf(-x)); }
; __device__ __forceinline__ void lru_pass(LAS unsigned char* L, int mode, const bf16_t* Z, const bf16_t* LWT, const float* conv_w, const float* conv_b, const float* b_a, const float* b_x, const float* lam,
;                          float* LSUM, const float* LCAR, bf16_t* Y) {
;     ...
;             for (int td = 0; td < 4; ++td) { const int d = td * 16 + fr, ch = n * 64 + d; const float lm = lam[g * 512 + ch]; const float sp = lm > 0.f ? log1pf(expf(-lm)) : -lm + log1pf(expf(lm));
;                 const float ba_ = b_a[g * 512 + ch], bx_ = b_x[g * 512 + ch];
; #pragma unroll
;                 for (int r = 0; r < 4; ++r) { const int i = ti * 16 + 4 * fq + r; const float la = -8.f * sigm(aa[td][r] + ba_) * sp;
;                     const float a_ = __expf(la), x2 = 2.f * la; const float om = (x2 > -0.02f) ? -x2 * (1.f + x2 * (0.5f + x2 * (1.f / 6.f))) : 1.f - a_ * a_;
;                     AA[g * 4160 + i * 65 + d] = a_; UU[g * 4160 + i * 65 + d] = __builtin_amdgcn_sqrtf(om) * sigm(ax[td][r] + bx_) * xc[i * 65 + d]; } } }
.LBB0_606:
	s_or_b64 exec, exec, s[20:21]
	v_lshlrev_b32_e32 v38, 2, v196
	v_add_u32_e32 v38, 0x21eb0, v38
	ds_write_b32 v38, v54 offset:0
	s_branch .Llru_c0_c
.Llru_c0_b:
	v_lshlrev_b32_e32 v38, 2, v196
	v_add_u32_e32 v38, 0x21eb0, v38
	ds_read_b32 v54, v38 offset:0
	ds_read_b32 v36, v38 offset:2048
	ds_read_b32 v37, v38 offset:4096
	s_waitcnt lgkmcnt(0)
.Llru_c0_c:
	v_lshlrev_b64 v[52:53], 2, v[52:53]
	v_lshl_add_u64 v[206:207], s[50:51], 0, v[52:53]
	s_cmp_lg_u32 s98, 0
	s_cbranch_scc1 .Llru_c0_d0
	global_load_dword v36, v[206:207], off
.Llru_c0_d0:
	v_lshl_add_u64 v[52:53], s[52:53], 0, v[52:53]
	s_cmp_lg_u32 s98, 0
	s_cbranch_scc1 .Llru_c0_d1
	global_load_dword v37, v[52:53], off
.Llru_c0_d1:
	s_mov_b32 s6, 0xc1000000
	s_mov_b32 s3, 0x3e2aaaab
	s_mov_b32 s4, 0xbca3d70a
	v_ashrrev_i32_e32 v51, 31, v50
	s_waitcnt vmcnt(1)
	v_add_f32_e32 v30, v30, v36
	v_mul_f32_e32 v30, 0xbfb8aa3b, v30
	v_exp_f32_e32 v30, v30
	s_waitcnt vmcnt(0)
	s_cmp_lg_u32 s98, 0
	s_cbranch_scc1 .Llru_c0_e
	v_lshlrev_b32_e32 v38, 2, v196
	v_add_u32_e32 v38, 0x21eb0, v38
	ds_write_b32 v38, v36 offset:2048
	ds_write_b32 v38, v37 offset:4096
.Llru_c0_e:
	v_add_f32_e32 v26, v26, v37
	v_mul_f32_e32 v26, 0xbfb8aa3b, v26
	v_exp_f32_e32 v26, v26
	v_add_f32_e32 v30, 1.0, v30
	v_rcp_f32_e32 v53, v30
	v_add_f32_e32 v30, v31, v36
	v_mul_f32_e32 v30, 0xbfb8aa3b, v30
	v_exp_f32_e32 v30, v30
	v_add_f32_e32 v26, 1.0, v26
	v_rcp_f32_e32 v26, v26
	v_add_f32_e32 v27, v27, v37
	v_add_f32_e32 v30, 1.0, v30
	v_rcp_f32_e32 v52, v30
	v_mul_f32_e32 v27, 0xbfb8aa3b, v27
	v_exp_f32_e32 v27, v27
	v_pk_mul_f32 v[30:31], v[52:53], s[6:7] op_sel_hi:[1,0]
	s_nop 0
	v_pk_mul_f32 v[30:31], v[54:55], v[30:31] op_sel_hi:[0,1]
	v_mul_f32_e32 v38, 0x3fb8aa3b, v31
	v_exp_f32_e32 v38, v38
	v_pk_add_f32 v[52:53], v[30:31], v[30:31]
	v_add_f32_e32 v27, 1.0, v27
	v_fma_f32 v31, v53, s3, 0.5
	v_fma_f32 v31, v53, v31, 1.0
	v_mul_f32_e64 v31, v31, -v53
	v_fma_f32 v39, -v38, v38, 1.0
	v_cmp_lt_f32_e64 s[44:45], s4, v53
	ds_write_b32 v68, v38 offset:62720
	v_cmp_lt_f32_e32 vcc, s4, v52
	v_cndmask_b32_e64 v31, v39, v31, s[44:45]
	v_sqrt_f32_e32 v31, v31
	v_rcp_f32_e32 v27, v27
	v_mul_f32_e32 v26, v26, v31
	ds_read_b32 v31, v69
	s_waitcnt lgkmcnt(0)
	v_mul_f32_e32 v26, v31, v26
	ds_write_b32 v70, v26
	v_mul_f32_e32 v26, 0x3fb8aa3b, v30
	v_exp_f32_e32 v26, v26
	v_fma_f32 v30, v52, s3, 0.5
	v_fma_f32 v30, v52, v30, 1.0
	v_mul_f32_e64 v30, v30, -v52
	v_fma_f32 v31, -v26, v26, 1.0
	v_cndmask_b32_e32 v30, v31, v30, vcc
	ds_write_b32 v68, v26 offset:62980
	v_sqrt_f32_e32 v26, v30
	s_nop 0
	v_mul_f32_e32 v26, v27, v26
	ds_read_b32 v27, v69 offset:260
	s_waitcnt lgkmcnt(0)
	v_mul_f32_e32 v26, v27, v26
	ds_write_b32 v71, v26
	v_add_f32_e32 v26, v32, v36
	v_mul_f32_e32 v26, 0xbfb8aa3b, v26
	v_exp_f32_e32 v26, v26
	s_nop 0
	v_add_f32_e32 v26, 1.0, v26
	v_rcp_f32_e32 v27, v26
	v_add_f32_e32 v26, v28, v37
	v_mul_f32_e32 v26, 0xbfb8aa3b, v26
	v_exp_f32_e32 v26, v26
	s_nop 0
	v_add_f32_e32 v26, 1.0, v26
	v_rcp_f32_e32 v28, v26
	v_add_f32_e32 v26, v33, v36
	v_mul_f32_e32 v26, 0xbfb8aa3b, v26
	v_exp_f32_e32 v26, v26
	s_nop 0
	v_add_f32_e32 v26, 1.0, v26
	v_rcp_f32_e32 v26, v26
	s_nop 0
	v_pk_mul_f32 v[26:27], v[26:27], s[6:7] op_sel_hi:[1,0]
	s_nop 0
	v_pk_mul_f32 v[26:27], v[54:55], v[26:27] op_sel_hi:[0,1]
	v_mul_f32_e32 v30, 0x3fb8aa3b, v27
	v_exp_f32_e32 v32, v30
	v_pk_add_f32 v[30:31], v[26:27], v[26:27]
	v_mul_f32_e32 v26, 0x3fb8aa3b, v26
	v_fma_f32 v27, v31, s3, 0.5
	v_fma_f32 v27, v31, v27, 1.0
	v_mul_f32_e64 v27, v27, -v31
	v_fma_f32 v33, -v32, v32, 1.0
	v_cmp_lt_f32_e64 s[44:45], s4, v31
	ds_write_b32 v68, v32 offset:63240
	v_exp_f32_e32 v26, v26
	v_cndmask_b32_e64 v27, v33, v27, s[44:45]
	v_sqrt_f32_e32 v27, v27
	v_cmp_lt_f32_e32 vcc, s4, v30
	v_mul_f32_e32 v27, v28, v27
	ds_read_b32 v28, v69 offset:520
	s_waitcnt lgkmcnt(0)
	v_mul_f32_e32 v27, v28, v27
	ds_write_b32 v72, v27
	v_fma_f32 v27, v30, s3, 0.5
	v_fma_f32 v27, v30, v27, 1.0
	v_mul_f32_e64 v27, v27, -v30
	v_fma_f32 v28, -v26, v26, 1.0
	v_cndmask_b32_e32 v27, v28, v27, vcc
	ds_write_b32 v68, v26 offset:63500
	v_sqrt_f32_e32 v26, v27
	v_add_f32_e32 v27, v29, v37
	v_mul_f32_e32 v27, 0xbfb8aa3b, v27
	v_exp_f32_e32 v27, v27
	v_lshl_add_u64 v[28:29], v[50:51], 0, v[34:35]
	v_add_f32_e32 v27, 1.0, v27
	v_rcp_f32_e32 v27, v27
	s_nop 0
	v_mul_f32_e32 v26, v27, v26
	ds_read_b32 v27, v69 offset:780
	s_waitcnt lgkmcnt(0)
	v_mul_f32_e32 v26, v27, v26
	ds_write_b32 v73, v26
	v_lshl_add_u64 v[26:27], v[28:29], 2, s[54:55]
	s_cmp_lg_u32 s98, 0
	s_cbranch_scc1 .Llru_c1_a
	global_load_dword v30, v[26:27], off offset:64
; __device__ __forceinline__ void lru_pass(LAS unsigned char* L, int mode, const bf16_t* Z, const bf16_t* LWT, const float* conv_w, const float* conv_b, const float* b_a, const float* b_x, const float* lam,
;                          float* LSUM, const float* LCAR, bf16_t* Y) {
;     ...
;             for (int td = 0; td < 4; ++td) { const int d = td * 16 + fr, ch = n * 64 + d; const float lm = lam[g * 512 + ch]; const float sp = lm > 0.f ? log1pf(expf(-lm)) : -lm + log1pf(expf(lm));
.Llru_c1_a:
	s_cmp_lg_u32 s98, 0
	s_cbranch_scc1 .Llru_c1_b
	s_waitcnt vmcnt(0)
	v_cmp_nlt_f32_e32 vcc, 0, v30
	s_and_saveexec_b64 s[4:5], vcc
	s_xor_b64 s[20:21], exec, s[4:5]
	s_cbranch_execz .LBB0_608
	v_mul_f32_e32 v31, 0x3fb8aa3b, v30
	v_rndne_f32_e32 v32, v31
	v_sub_f32_e32 v33, v31, v32
	v_fma_f32 v31, v30, s15, -v31
	v_fmac_f32_e32 v31, 0x32a5705f, v30
	v_add_f32_e32 v31, v33, v31
	v_cvt_i32_f32_e32 v32, v32
	v_exp_f32_e32 v31, v31
	s_mov_b32 s3, 0xc2ce8ed0
	v_cmp_ngt_f32_e32 vcc, s3, v30
	s_mov_b32 s3, 0x42b17218
	v_ldexp_f32 v31, v31, v32
	v_cndmask_b32_e32 v31, 0, v31, vcc
	v_cmp_nlt_f32_e32 vcc, s3, v30
	s_mov_b32 s3, 0x33800000
	s_nop 0
	v_cndmask_b32_e32 v31, v222, v31, vcc
	v_add_f32_e32 v36, 1.0, v31
	v_add_f32_e32 v32, -1.0, v36
	v_sub_f32_e32 v33, v32, v36
	v_add_f32_e32 v33, 1.0, v33
	v_sub_f32_e32 v32, v31, v32
	v_add_f32_e32 v37, v32, v33
	v_frexp_mant_f32_e32 v38, v36
	v_cvt_f64_f32_e32 v[32:33], v36
	v_frexp_exp_i32_f64_e32 v32, v[32:33]
	v_cmp_gt_f32_e32 vcc, s11, v38
	s_nop 1
	v_subbrev_co_u32_e32 v38, vcc, 0, v32, vcc
	v_sub_u32_e32 v32, 0, v38
	v_ldexp_f32 v33, v36, v32
	v_add_f32_e32 v36, -1.0, v33
	v_add_f32_e32 v39, 1.0, v33
	v_ldexp_f32 v32, v37, v32
	v_add_f32_e32 v37, 1.0, v36
	v_add_f32_e32 v42, -1.0, v39
	v_sub_f32_e32 v37, v33, v37
	v_sub_f32_e32 v33, v33, v42
	v_add_f32_e32 v37, v32, v37
	v_add_f32_e32 v32, v32, v33
	v_add_f32_e32 v42, v39, v32
	v_rcp_f32_e32 v43, v42
	v_sub_f32_e32 v33, v39, v42
	v_add_f32_e32 v39, v32, v33
	v_add_f32_e32 v33, v36, v37
	v_sub_f32_e32 v32, v36, v33
	v_add_f32_e32 v36, v37, v32
	v_mul_f32_e32 v37, v33, v43
	v_mul_f32_e32 v50, v42, v37
	v_fma_f32 v52, v37, v42, -v50
	v_fmac_f32_e32 v52, v37, v39
	v_add_f32_e32 v32, v50, v52
	v_sub_f32_e32 v51, v33, v32
	v_pk_add_f32 v[206:207], v[32:33], v[50:51] neg_lo:[0,1] neg_hi:[0,1]
	v_mov_b32_e32 v53, v32
	v_pk_add_f32 v[32:33], v[206:207], v[52:53] neg_lo:[0,1] neg_hi:[0,1]
	v_cmp_neq_f32_e32 vcc, s2, v31
	v_add_f32_e32 v33, v36, v33
	v_add_f32_e32 v32, v32, v33
	v_add_f32_e32 v33, v51, v32
	v_mul_f32_e32 v36, v43, v33
	v_mul_f32_e32 v50, v42, v36
	v_fma_f32 v52, v36, v42, -v50
	v_fmac_f32_e32 v52, v36, v39
	v_sub_f32_e32 v39, v51, v33
	v_add_f32_e32 v39, v32, v39
	v_add_f32_e32 v32, v50, v52
	v_sub_f32_e32 v51, v33, v32
	v_pk_add_f32 v[206:207], v[32:33], v[50:51] neg_lo:[0,1] neg_hi:[0,1]
	v_mov_b32_e32 v53, v32
	v_pk_add_f32 v[32:33], v[206:207], v[52:53] neg_lo:[0,1] neg_hi:[0,1]
	s_nop 0
	v_add_f32_e32 v33, v39, v33
	v_add_f32_e32 v32, v32, v33
	v_add_f32_e32 v33, v37, v36
	v_add_f32_e32 v32, v51, v32
	v_sub_f32_e32 v37, v33, v37
	v_mul_f32_e32 v32, v43, v32
	v_sub_f32_e32 v36, v36, v37
	v_add_f32_e32 v36, v36, v32
	v_add_f32_e32 v37, v33, v36
	v_mul_f32_e32 v39, v37, v37
	v_fmamk_f32 v32, v39, 0x3e9b6dac, v220
	v_fmaak_f32 v155, v39, v32, 0x3f2aaada
	v_cvt_f32_i32_e32 v32, v38
	v_sub_f32_e32 v33, v37, v33
	v_sub_f32_e32 v33, v36, v33
	v_ldexp_f32 v36, v33, 1
	v_mul_f32_e32 v33, v37, v39
	v_pk_mul_f32 v[52:53], v[32:33], v[154:155]
	v_ldexp_f32 v51, v37, 1
	v_fma_f32 v50, v32, s14, -v52
	v_fmac_f32_e32 v50, 0xb102e308, v32
	v_pk_add_f32 v[32:33], v[52:53], v[50:51]
	v_mov_b32_e32 v206, v52
	v_sub_f32_e32 v37, v33, v51
	v_sub_f32_e32 v37, v53, v37
	v_add_f32_e32 v207, v36, v37
	v_pk_add_f32 v[52:53], v[32:33], v[52:53] neg_lo:[0,1] neg_hi:[0,1]
	v_pk_add_f32 v[208:209], v[32:33], v[206:207]
	v_mov_b32_e32 v51, v32
	v_mov_b32_e32 v53, v209
	v_pk_add_f32 v[210:211], v[50:51], v[52:53] neg_lo:[0,1] neg_hi:[0,1]
	v_pk_add_f32 v[50:51], v[50:51], v[52:53]
	v_mov_b32_e32 v206, v207
	v_pk_add_f32 v[52:53], v[50:51], v[32:33] op_sel:[1,0] op_sel_hi:[0,1] neg_lo:[0,1] neg_hi:[0,1]
	v_pk_add_f32 v[212:213], v[208:209], v[52:53] op_sel_hi:[1,0] neg_lo:[0,1] neg_hi:[0,1]
	v_mov_b32_e32 v208, v209
	v_mov_b32_e32 v209, v51
	v_pk_mov_b32 v[52:53], v[32:33], v[52:53] op_sel:[1,0]
	v_mov_b32_e32 v207, v32
	v_pk_add_f32 v[52:53], v[208:209], v[52:53] neg_lo:[0,1] neg_hi:[0,1]
	v_mov_b32_e32 v212, v210
	v_pk_add_f32 v[32:33], v[206:207], v[52:53] neg_lo:[0,1] neg_hi:[0,1]
	v_mov_b32_e32 v211, v51
	v_pk_add_f32 v[52:53], v[212:213], v[32:33]
	s_nop 0
	v_pk_add_f32 v[206:207], v[52:53], v[52:53] op_sel:[0,1] op_sel_hi:[1,0]
	s_nop 0
	v_pk_add_f32 v[50:51], v[50:51], v[206:207] op_sel:[1,0] op_sel_hi:[0,1]
	v_mov_b32_e32 v53, v50
	v_pk_add_f32 v[208:209], v[52:53], v[210:211] neg_lo:[0,1] neg_hi:[0,1]
	v_mov_b32_e32 v33, v206
	v_sub_f32_e32 v36, v52, v208
	v_pk_add_f32 v[32:33], v[32:33], v[208:209] neg_lo:[0,1] neg_hi:[0,1]
	v_sub_f32_e32 v36, v210, v36
	v_add_f32_e32 v32, v32, v36
	v_add_f32_e32 v32, v32, v33
	v_add_f32_e32 v32, v50, v32
	v_cndmask_b32_e32 v32, v222, v32, vcc
	v_cmp_lt_f32_e64 vcc, |v31|, s3
	s_nop 1
	v_cndmask_b32_e32 v31, v32, v31, vcc
	v_sub_f32_e32 v32, v31, v30

; __device__ __forceinline__ float sigm(float x) { return __builtin_amdgcn_rcpf(1.f + __expf(-x)); }
; __device__ __forceinline__ void lru_pass(LAS unsigned char* L, int mode, const bf16_t* Z, const bf16_t* LWT, const float* conv_w, const float* conv_b, const float* b_a, const float* b_x, const float* lam,
;                          float* LSUM, const float* LCAR, bf16_t* Y) {
;     ...
;             for (int td = 0; td < 4; ++td) { const int d = td * 16 + fr, ch = n * 64 + d; const float lm = lam[g * 512 + ch]; const float sp = lm > 0.f ? log1pf(expf(-lm)) : -lm + log1pf(expf(lm));
;                 const float ba_ = b_a[g * 512 + ch], bx_ = b_x[g * 512 + ch];
; #pragma unroll
;                 for (int r = 0; r < 4; ++r) { const int i = ti * 16 + 4 * fq + r; const float la = -8.f * sigm(aa[td][r] + ba_) * sp;
;                     const float a_ = __expf(la), x2 = 2.f * la; const float om = (x2 > -0.02f) ? -x2 * (1.f + x2 * (0.5f + x2 * (1.f / 6.f))) : 1.f - a_ * a_;
;                     AA[g * 4160 + i * 65 + d] = a_; UU[g * 4160 + i * 65 + d] = __builtin_amdgcn_sqrtf(om) * sigm(ax[td][r] + bx_) * xc[i * 65 + d]; } } }
.LBB0_610:
	s_or_b64 exec, exec, s[20:21]
	v_lshlrev_b32_e32 v38, 2, v196
	v_add_u32_e32 v38, 0x21eb0, v38
	ds_write_b32 v38, v32 offset:6144
	s_branch .Llru_c1_c
.Llru_c1_b:
	v_lshlrev_b32_e32 v38, 2, v196
	v_add_u32_e32 v38, 0x21eb0, v38
	ds_read_b32 v32, v38 offset:6144
	ds_read_b32 v33, v38 offset:8192
	ds_read_b32 v36, v38 offset:10240
	s_waitcnt lgkmcnt(0)
.Llru_c1_c:
	v_lshlrev_b64 v[30:31], 2, v[28:29]
	v_lshl_add_u64 v[28:29], s[50:51], 0, v[30:31]
	s_cmp_lg_u32 s98, 0
	s_cbranch_scc1 .Llru_c1_d0
	global_load_dword v33, v[28:29], off offset:64
.Llru_c1_d0:
	v_lshl_add_u64 v[30:31], s[52:53], 0, v[30:31]
	s_cmp_lg_u32 s98, 0
	s_cbranch_scc1 .Llru_c1_d1
	global_load_dword v36, v[30:31], off offset:64
.Llru_c1_d1:
	s_mov_b32 s3, 0x3e2aaaab
	s_mov_b32 s4, 0xbca3d70a
	s_waitcnt vmcnt(1)
	v_add_f32_e32 v22, v22, v33
	v_mul_f32_e32 v22, 0xbfb8aa3b, v22
	v_exp_f32_e32 v22, v22
	s_waitcnt vmcnt(0)
	s_cmp_lg_u32 s98, 0
	s_cbranch_scc1 .Llru_c1_e
	v_lshlrev_b32_e32 v38, 2, v196
	v_add_u32_e32 v38, 0x21eb0, v38
	ds_write_b32 v38, v33 offset:8192
	ds_write_b32 v38, v36 offset:10240
.Llru_c1_e:
	v_add_f32_e32 v18, v18, v36
	v_mul_f32_e32 v18, 0xbfb8aa3b, v18
	v_exp_f32_e32 v18, v18
	v_add_f32_e32 v22, 1.0, v22
	v_rcp_f32_e32 v51, v22
	v_add_f32_e32 v22, v23, v33
	v_mul_f32_e32 v22, 0xbfb8aa3b, v22
	v_exp_f32_e32 v22, v22
	v_add_f32_e32 v18, 1.0, v18
	v_rcp_f32_e32 v18, v18
	v_add_f32_e32 v19, v19, v36
	v_add_f32_e32 v22, 1.0, v22
	v_rcp_f32_e32 v50, v22
	v_mul_f32_e32 v19, 0xbfb8aa3b, v19
	v_exp_f32_e32 v19, v19
	v_pk_mul_f32 v[22:23], v[50:51], s[6:7] op_sel_hi:[1,0]
	s_nop 0
	v_pk_mul_f32 v[22:23], v[32:33], v[22:23] op_sel_hi:[0,1]
	v_mul_f32_e32 v37, 0x3fb8aa3b, v23
	v_exp_f32_e32 v37, v37
	v_pk_add_f32 v[50:51], v[22:23], v[22:23]
	v_add_f32_e32 v19, 1.0, v19
	v_fma_f32 v23, v51, s3, 0.5
	v_fma_f32 v23, v51, v23, 1.0
	v_mul_f32_e64 v23, v23, -v51
	v_fma_f32 v38, -v37, v37, 1.0
	v_cmp_lt_f32_e64 s[44:45], s4, v51
	ds_write_b32 v68, v37 offset:62784
	v_cmp_lt_f32_e32 vcc, s4, v50
	v_cndmask_b32_e64 v23, v38, v23, s[44:45]
	v_sqrt_f32_e32 v23, v23
	v_rcp_f32_e32 v19, v19
	v_mul_f32_e32 v18, v18, v23
	ds_read_b32 v23, v69 offset:64
	s_waitcnt lgkmcnt(0)
	v_mul_f32_e32 v18, v23, v18
	ds_write_b32 v74, v18
	v_mul_f32_e32 v18, 0x3fb8aa3b, v22
	v_exp_f32_e32 v18, v18
	v_fma_f32 v22, v50, s3, 0.5
	v_fma_f32 v22, v50, v22, 1.0
	v_mul_f32_e64 v22, v22, -v50
	v_fma_f32 v23, -v18, v18, 1.0
	v_cndmask_b32_e32 v22, v23, v22, vcc
	ds_write_b32 v75, v18 offset:62980
	v_sqrt_f32_e32 v18, v22
	s_nop 0
	v_mul_f32_e32 v18, v19, v18
	ds_read_b32 v19, v69 offset:324
	s_waitcnt lgkmcnt(0)
	v_mul_f32_e32 v18, v19, v18
	ds_write_b32 v76, v18
	v_add_f32_e32 v18, v24, v33
	v_mul_f32_e32 v18, 0xbfb8aa3b, v18
	v_exp_f32_e32 v18, v18
	s_nop 0
	v_add_f32_e32 v18, 1.0, v18
	v_rcp_f32_e32 v19, v18
	v_add_f32_e32 v18, v20, v36
	v_mul_f32_e32 v18, 0xbfb8aa3b, v18
	v_exp_f32_e32 v18, v18
	s_nop 0
	v_add_f32_e32 v18, 1.0, v18
	v_rcp_f32_e32 v20, v18
	v_add_f32_e32 v18, v25, v33
	v_mul_f32_e32 v18, 0xbfb8aa3b, v18
	v_exp_f32_e32 v18, v18
	s_nop 0
	v_add_f32_e32 v18, 1.0, v18
	v_rcp_f32_e32 v18, v18
	s_nop 0
	v_pk_mul_f32 v[18:19], v[18:19], s[6:7] op_sel_hi:[1,0]
	s_nop 0
	v_pk_mul_f32 v[18:19], v[32:33], v[18:19] op_sel_hi:[0,1]
	v_mul_f32_e32 v22, 0x3fb8aa3b, v19
	v_exp_f32_e32 v24, v22
	v_pk_add_f32 v[22:23], v[18:19], v[18:19]
	v_mul_f32_e32 v18, 0x3fb8aa3b, v18
	v_fma_f32 v19, v23, s3, 0.5
	v_fma_f32 v19, v23, v19, 1.0
	v_mul_f32_e64 v19, v19, -v23
	v_fma_f32 v25, -v24, v24, 1.0
	v_cmp_lt_f32_e64 s[44:45], s4, v23
	ds_write_b32 v75, v24 offset:63240
	v_exp_f32_e32 v18, v18
	v_cndmask_b32_e64 v19, v25, v19, s[44:45]
	v_sqrt_f32_e32 v19, v19
	v_cmp_lt_f32_e32 vcc, s4, v22
	v_mul_f32_e32 v19, v20, v19
	ds_read_b32 v20, v69 offset:584
	s_waitcnt lgkmcnt(0)
	v_mul_f32_e32 v19, v20, v19
	ds_write_b32 v77, v19
	v_fma_f32 v19, v22, s3, 0.5
	v_fma_f32 v19, v22, v19, 1.0
	v_mul_f32_e64 v19, v19, -v22
	v_fma_f32 v20, -v18, v18, 1.0
	v_cndmask_b32_e32 v19, v20, v19, vcc
	ds_write_b32 v75, v18 offset:63500
	v_sqrt_f32_e32 v18, v19
	v_add_f32_e32 v19, v21, v36
	v_mul_f32_e32 v19, 0xbfb8aa3b, v19
	v_exp_f32_e32 v19, v19
	s_nop 0
	v_add_f32_e32 v19, 1.0, v19
	v_rcp_f32_e32 v19, v19
	s_nop 0
	v_mul_f32_e32 v18, v19, v18
	ds_read_b32 v19, v69 offset:844
	s_waitcnt lgkmcnt(0)
	v_mul_f32_e32 v18, v19, v18
	s_cmp_lg_u32 s98, 0
	s_cbranch_scc1 .Llru_c2_a
	global_load_dword v19, v[26:27], off offset:128
; __device__ __forceinline__ void lru_pass(LAS unsigned char* L, int mode, const bf16_t* Z, const bf16_t* LWT, const float* conv_w, const float* conv_b, const float* b_a, const float* b_x, const float* lam,
;                          float* LSUM, const float* LCAR, bf16_t* Y) {
;     ...
;             for (int td = 0; td < 4; ++td) { const int d = td * 16 + fr, ch = n * 64 + d; const float lm = lam[g * 512 + ch]; const float sp = lm > 0.f ? log1pf(expf(-lm)) : -lm + log1pf(expf(lm));
.Llru_c2_a:
	ds_write_b32 v78, v18
	s_cmp_lg_u32 s98, 0
	s_cbranch_scc1 .Llru_c2_b
	s_waitcnt vmcnt(0)
	v_cmp_nlt_f32_e32 vcc, 0, v19
	s_and_saveexec_b64 s[4:5], vcc
	s_xor_b64 s[20:21], exec, s[4:5]
	s_cbranch_execz .LBB0_612
	v_mul_f32_e32 v18, 0x3fb8aa3b, v19
	v_rndne_f32_e32 v20, v18
	v_sub_f32_e32 v21, v18, v20
	v_fma_f32 v18, v19, s15, -v18
	v_fmac_f32_e32 v18, 0x32a5705f, v19
	v_add_f32_e32 v18, v21, v18
	v_cvt_i32_f32_e32 v20, v20
	v_exp_f32_e32 v18, v18
	s_mov_b32 s3, 0xc2ce8ed0
	v_cmp_ngt_f32_e32 vcc, s3, v19
	s_mov_b32 s3, 0x42b17218
	v_ldexp_f32 v18, v18, v20
	v_cndmask_b32_e32 v18, 0, v18, vcc
	v_cmp_nlt_f32_e32 vcc, s3, v19
	s_mov_b32 s3, 0x33800000
	s_nop 0
	v_cndmask_b32_e32 v18, v222, v18, vcc
	v_add_f32_e32 v22, 1.0, v18
	v_add_f32_e32 v20, -1.0, v22
	v_sub_f32_e32 v21, v20, v22
	v_add_f32_e32 v21, 1.0, v21
	v_sub_f32_e32 v20, v18, v20
	v_add_f32_e32 v23, v20, v21
	v_frexp_mant_f32_e32 v24, v22
	v_cvt_f64_f32_e32 v[20:21], v22
	v_frexp_exp_i32_f64_e32 v20, v[20:21]
	v_cmp_gt_f32_e32 vcc, s11, v24
	s_nop 1
	v_subbrev_co_u32_e32 v36, vcc, 0, v20, vcc
	v_sub_u32_e32 v20, 0, v36
	v_ldexp_f32 v21, v22, v20
	v_add_f32_e32 v22, -1.0, v21
	v_add_f32_e32 v24, 1.0, v21
	v_ldexp_f32 v20, v23, v20
	v_add_f32_e32 v23, 1.0, v22
	v_add_f32_e32 v25, -1.0, v24
	v_sub_f32_e32 v23, v21, v23
	v_sub_f32_e32 v21, v21, v25
	v_add_f32_e32 v23, v20, v23
	v_add_f32_e32 v20, v20, v21
	v_add_f32_e32 v37, v24, v20
	v_rcp_f32_e32 v39, v37
	v_sub_f32_e32 v21, v24, v37
	v_add_f32_e32 v38, v20, v21
	v_add_f32_e32 v21, v22, v23
	v_mul_f32_e32 v43, v21, v39
	v_sub_f32_e32 v20, v22, v21
	v_mul_f32_e32 v22, v37, v43
	v_fma_f32 v24, v43, v37, -v22
	v_fmac_f32_e32 v24, v43, v38
	v_add_f32_e32 v42, v23, v20
	v_add_f32_e32 v20, v22, v24
	v_sub_f32_e32 v23, v21, v20
	v_pk_add_f32 v[32:33], v[20:21], v[22:23] neg_lo:[0,1] neg_hi:[0,1]
	v_mov_b32_e32 v25, v20
	v_pk_add_f32 v[20:21], v[32:33], v[24:25] neg_lo:[0,1] neg_hi:[0,1]
	v_cmp_neq_f32_e32 vcc, s2, v18
	v_add_f32_e32 v21, v42, v21
	v_add_f32_e32 v20, v20, v21
	v_add_f32_e32 v21, v23, v20
	v_mul_f32_e32 v42, v39, v21
	v_mul_f32_e32 v22, v37, v42
	v_fma_f32 v24, v42, v37, -v22
	v_fmac_f32_e32 v24, v42, v38
	v_sub_f32_e32 v23, v23, v21
	v_add_f32_e32 v37, v20, v23
	v_add_f32_e32 v20, v22, v24
	v_sub_f32_e32 v23, v21, v20
	v_pk_add_f32 v[32:33], v[20:21], v[22:23] neg_lo:[0,1] neg_hi:[0,1]
	v_mov_b32_e32 v25, v20
	v_pk_add_f32 v[20:21], v[32:33], v[24:25] neg_lo:[0,1] neg_hi:[0,1]
	s_nop 0
	v_add_f32_e32 v21, v37, v21
	v_add_f32_e32 v20, v20, v21
	v_add_f32_e32 v21, v43, v42
	v_add_f32_e32 v20, v23, v20
	v_sub_f32_e32 v22, v21, v43
	v_mul_f32_e32 v20, v39, v20
	v_sub_f32_e32 v22, v42, v22
	v_add_f32_e32 v22, v22, v20
	v_add_f32_e32 v24, v21, v22
	v_mul_f32_e32 v25, v24, v24
	v_fmamk_f32 v20, v25, 0x3e9b6dac, v220
	v_fmaak_f32 v155, v25, v20, 0x3f2aaada
	v_cvt_f32_i32_e32 v20, v36
	v_sub_f32_e32 v21, v24, v21
	v_sub_f32_e32 v21, v22, v21
	v_ldexp_f32 v32, v21, 1
	v_mul_f32_e32 v21, v24, v25
	v_ldexp_f32 v23, v24, 1
	v_pk_mul_f32 v[24:25], v[20:21], v[154:155]
	s_nop 0
	v_fma_f32 v22, v20, s14, -v24
	v_fmac_f32_e32 v22, 0xb102e308, v20
	v_pk_add_f32 v[20:21], v[24:25], v[22:23]
	s_nop 0
	v_sub_f32_e32 v23, v21, v23
	v_sub_f32_e32 v23, v25, v23
	v_add_f32_e32 v33, v32, v23
	v_mov_b32_e32 v32, v24
	v_pk_add_f32 v[24:25], v[20:21], v[24:25] neg_lo:[0,1] neg_hi:[0,1]
	v_pk_add_f32 v[50:51], v[20:21], v[32:33]
	v_mov_b32_e32 v23, v20
	v_mov_b32_e32 v25, v51
	v_pk_add_f32 v[52:53], v[22:23], v[24:25] neg_lo:[0,1] neg_hi:[0,1]
	v_pk_add_f32 v[22:23], v[22:23], v[24:25]
	v_mov_b32_e32 v32, v33
	v_pk_add_f32 v[24:25], v[22:23], v[20:21] op_sel:[1,0] op_sel_hi:[0,1] neg_lo:[0,1] neg_hi:[0,1]
	v_pk_add_f32 v[206:207], v[50:51], v[24:25] op_sel_hi:[1,0] neg_lo:[0,1] neg_hi:[0,1]
	v_mov_b32_e32 v50, v51
	v_mov_b32_e32 v51, v23
	v_pk_mov_b32 v[24:25], v[20:21], v[24:25] op_sel:[1,0]
	v_mov_b32_e32 v33, v20
	v_pk_add_f32 v[24:25], v[50:51], v[24:25] neg_lo:[0,1] neg_hi:[0,1]
	v_mov_b32_e32 v206, v52
	v_pk_add_f32 v[20:21], v[32:33], v[24:25] neg_lo:[0,1] neg_hi:[0,1]
	v_mov_b32_e32 v53, v23
	v_pk_add_f32 v[24:25], v[206:207], v[20:21]
	s_nop 0
	v_pk_add_f32 v[32:33], v[24:25], v[24:25] op_sel:[0,1] op_sel_hi:[1,0]
	s_nop 0
	v_pk_add_f32 v[22:23], v[22:23], v[32:33] op_sel:[1,0] op_sel_hi:[0,1]
	v_mov_b32_e32 v25, v22
	v_pk_add_f32 v[50:51], v[24:25], v[52:53] neg_lo:[0,1] neg_hi:[0,1]
	v_mov_b32_e32 v21, v32
	v_sub_f32_e32 v23, v24, v50
	v_pk_add_f32 v[20:21], v[20:21], v[50:51] neg_lo:[0,1] neg_hi:[0,1]
	v_sub_f32_e32 v23, v52, v23
	v_add_f32_e32 v20, v20, v23
	v_add_f32_e32 v20, v20, v21
	v_add_f32_e32 v20, v22, v20
	v_cndmask_b32_e32 v20, v222, v20, vcc
	v_cmp_lt_f32_e64 vcc, |v18|, s3
	s_nop 1
	v_cndmask_b32_e32 v18, v20, v18, vcc
	v_sub_f32_e32 v18, v18, v19

; __device__ __forceinline__ float sigm(float x) { return __builtin_amdgcn_rcpf(1.f + __expf(-x)); }
; __device__ __forceinline__ void lru_pass(LAS unsigned char* L, int mode, const bf16_t* Z, const bf16_t* LWT, const float* conv_w, const float* conv_b, const float* b_a, const float* b_x, const float* lam,
;                          float* LSUM, const float* LCAR, bf16_t* Y) {
;     ...
;             for (int td = 0; td < 4; ++td) { const int d = td * 16 + fr, ch = n * 64 + d; const float lm = lam[g * 512 + ch]; const float sp = lm > 0.f ? log1pf(expf(-lm)) : -lm + log1pf(expf(lm));
;                 const float ba_ = b_a[g * 512 + ch], bx_ = b_x[g * 512 + ch];
; #pragma unroll
;                 for (int r = 0; r < 4; ++r) { const int i = ti * 16 + 4 * fq + r; const float la = -8.f * sigm(aa[td][r] + ba_) * sp;
;                     const float a_ = __expf(la), x2 = 2.f * la; const float om = (x2 > -0.02f) ? -x2 * (1.f + x2 * (0.5f + x2 * (1.f / 6.f))) : 1.f - a_ * a_;
;                     AA[g * 4160 + i * 65 + d] = a_; UU[g * 4160 + i * 65 + d] = __builtin_amdgcn_sqrtf(om) * sigm(ax[td][r] + bx_) * xc[i * 65 + d]; } } }
.LBB0_614:
	s_or_b64 exec, exec, s[20:21]
	v_lshlrev_b32_e32 v38, 2, v196
	v_add_u32_e32 v38, 0x21eb0, v38
	ds_write_b32 v38, v18 offset:12288
	s_branch .Llru_c2_c
.Llru_c2_b:
	v_lshlrev_b32_e32 v38, 2, v196
	v_add_u32_e32 v38, 0x21eb0, v38
	ds_read_b32 v18, v38 offset:12288
	ds_read_b32 v19, v38 offset:14336
	ds_read_b32 v22, v38 offset:16384
	s_waitcnt lgkmcnt(0)
.Llru_c2_c:
	s_cmp_lg_u32 s98, 0
	s_cbranch_scc1 .Llru_c2_d0
	global_load_dword v19, v[28:29], off offset:128
.Llru_c2_d0:
	s_cmp_lg_u32 s98, 0
	s_cbranch_scc1 .Llru_c2_d1
	global_load_dword v22, v[30:31], off offset:128
.Llru_c2_d1:
	s_mov_b32 s3, 0x3e2aaaab
	s_mov_b32 s4, 0xbca3d70a
	s_waitcnt vmcnt(1)
	v_add_f32_e32 v14, v14, v19
	v_mul_f32_e32 v14, 0xbfb8aa3b, v14
	v_exp_f32_e32 v14, v14
	s_waitcnt vmcnt(0)
	s_cmp_lg_u32 s98, 0
	s_cbranch_scc1 .Llru_c2_e
	v_lshlrev_b32_e32 v38, 2, v196
	v_add_u32_e32 v38, 0x21eb0, v38
	ds_write_b32 v38, v19 offset:14336
	ds_write_b32 v38, v22 offset:16384
.Llru_c2_e:
	v_add_f32_e32 v10, v10, v22
	v_mul_f32_e32 v10, 0xbfb8aa3b, v10
	v_exp_f32_e32 v10, v10
	v_add_f32_e32 v14, 1.0, v14
	v_rcp_f32_e32 v21, v14
	v_add_f32_e32 v14, v15, v19
	v_mul_f32_e32 v14, 0xbfb8aa3b, v14
	v_exp_f32_e32 v14, v14
	v_add_f32_e32 v10, 1.0, v10
	v_rcp_f32_e32 v10, v10
	v_add_f32_e32 v11, v11, v22
	v_add_f32_e32 v14, 1.0, v14
	v_rcp_f32_e32 v20, v14
	v_mul_f32_e32 v11, 0xbfb8aa3b, v11
	v_exp_f32_e32 v11, v11
	v_pk_mul_f32 v[14:15], v[20:21], s[6:7] op_sel_hi:[1,0]
	s_nop 0
	v_pk_mul_f32 v[14:15], v[18:19], v[14:15] op_sel_hi:[0,1]
	v_mul_f32_e32 v20, 0x3fb8aa3b, v15
	v_exp_f32_e32 v23, v20
	v_pk_add_f32 v[20:21], v[14:15], v[14:15]
	v_add_f32_e32 v11, 1.0, v11
	v_fma_f32 v15, v21, s3, 0.5
	v_fma_f32 v15, v21, v15, 1.0
	v_mul_f32_e64 v15, v15, -v21
	v_fma_f32 v24, -v23, v23, 1.0
	v_cmp_lt_f32_e64 s[44:45], s4, v21
	ds_write_b32 v68, v23 offset:62848
	v_cmp_lt_f32_e32 vcc, s4, v20
	v_cndmask_b32_e64 v15, v24, v15, s[44:45]
	v_sqrt_f32_e32 v15, v15
	v_rcp_f32_e32 v11, v11
	v_mul_f32_e32 v10, v10, v15
	ds_read_b32 v15, v69 offset:128
	s_waitcnt lgkmcnt(0)
	v_mul_f32_e32 v10, v15, v10
	ds_write_b32 v79, v10
	v_mul_f32_e32 v10, 0x3fb8aa3b, v14
	v_exp_f32_e32 v10, v10
	v_fma_f32 v14, v20, s3, 0.5
	v_fma_f32 v14, v20, v14, 1.0
	v_mul_f32_e64 v14, v14, -v20
	v_fma_f32 v15, -v10, v10, 1.0
	v_cndmask_b32_e32 v14, v15, v14, vcc
	ds_write_b32 v80, v10 offset:62980
	v_sqrt_f32_e32 v10, v14
	s_nop 0
	v_mul_f32_e32 v10, v11, v10
	ds_read_b32 v11, v69 offset:388
	s_waitcnt lgkmcnt(0)
	v_mul_f32_e32 v10, v11, v10
	ds_write_b32 v81, v10
	v_add_f32_e32 v10, v16, v19
	v_mul_f32_e32 v10, 0xbfb8aa3b, v10
	v_exp_f32_e32 v10, v10
	s_nop 0
	v_add_f32_e32 v10, 1.0, v10
	v_rcp_f32_e32 v11, v10
	v_add_f32_e32 v10, v12, v22
	v_mul_f32_e32 v10, 0xbfb8aa3b, v10
	v_exp_f32_e32 v10, v10
	s_nop 0
	v_add_f32_e32 v10, 1.0, v10
	v_rcp_f32_e32 v12, v10
	v_add_f32_e32 v10, v17, v19
	v_mul_f32_e32 v10, 0xbfb8aa3b, v10
	v_exp_f32_e32 v10, v10
	s_nop 0
	v_add_f32_e32 v10, 1.0, v10
	v_rcp_f32_e32 v10, v10
	s_nop 0
	v_pk_mul_f32 v[10:11], v[10:11], s[6:7] op_sel_hi:[1,0]
	s_nop 0
	v_pk_mul_f32 v[10:11], v[18:19], v[10:11] op_sel_hi:[0,1]
	v_mul_f32_e32 v14, 0x3fb8aa3b, v11
	v_exp_f32_e32 v16, v14
	v_pk_add_f32 v[14:15], v[10:11], v[10:11]
	v_mul_f32_e32 v10, 0x3fb8aa3b, v10
	v_fma_f32 v11, v15, s3, 0.5
	v_fma_f32 v11, v15, v11, 1.0
	v_mul_f32_e64 v11, v11, -v15
	v_fma_f32 v17, -v16, v16, 1.0
	v_cmp_lt_f32_e64 s[44:45], s4, v15
	ds_write_b32 v80, v16 offset:63240
	v_exp_f32_e32 v10, v10
	v_cndmask_b32_e64 v11, v17, v11, s[44:45]
	v_sqrt_f32_e32 v11, v11
	v_cmp_lt_f32_e32 vcc, s4, v14
	v_mul_f32_e32 v11, v12, v11
	ds_read_b32 v12, v69 offset:648
	s_waitcnt lgkmcnt(0)
	v_mul_f32_e32 v11, v12, v11
	ds_write_b32 v82, v11
	v_fma_f32 v11, v14, s3, 0.5
	v_fma_f32 v11, v14, v11, 1.0
	v_mul_f32_e64 v11, v11, -v14
	v_fma_f32 v12, -v10, v10, 1.0
	v_cndmask_b32_e32 v11, v12, v11, vcc
	ds_write_b32 v80, v10 offset:63500
	v_sqrt_f32_e32 v10, v11
	v_add_f32_e32 v11, v13, v22
	v_mul_f32_e32 v11, 0xbfb8aa3b, v11
	v_exp_f32_e32 v11, v11
	s_nop 0
	v_add_f32_e32 v11, 1.0, v11
	v_rcp_f32_e32 v11, v11
	s_nop 0
	v_mul_f32_e32 v10, v11, v10
	ds_read_b32 v11, v69 offset:908
	s_waitcnt lgkmcnt(0)
	v_mul_f32_e32 v10, v11, v10
	s_cmp_lg_u32 s98, 0
	s_cbranch_scc1 .Llru_c3_a
	global_load_dword v11, v[26:27], off offset:192
; __device__ __forceinline__ void lru_pass(LAS unsigned char* L, int mode, const bf16_t* Z, const bf16_t* LWT, const float* conv_w, const float* conv_b, const float* b_a, const float* b_x, const float* lam,
;                          float* LSUM, const float* LCAR, bf16_t* Y) {
;     ...
;             for (int td = 0; td < 4; ++td) { const int d = td * 16 + fr, ch = n * 64 + d; const float lm = lam[g * 512 + ch]; const float sp = lm > 0.f ? log1pf(expf(-lm)) : -lm + log1pf(expf(lm));
.Llru_c3_a:
	ds_write_b32 v83, v10
	s_cmp_lg_u32 s98, 0
	s_cbranch_scc1 .Llru_c3_b
	s_waitcnt vmcnt(0)
	v_cmp_nlt_f32_e32 vcc, 0, v11
	s_and_saveexec_b64 s[4:5], vcc
	s_xor_b64 s[20:21], exec, s[4:5]
	s_cbranch_execz .LBB0_616
	v_mul_f32_e32 v10, 0x3fb8aa3b, v11
	v_rndne_f32_e32 v12, v10
	v_sub_f32_e32 v13, v10, v12
	v_fma_f32 v10, v11, s15, -v10
	v_fmac_f32_e32 v10, 0x32a5705f, v11
	v_add_f32_e32 v10, v13, v10
	v_cvt_i32_f32_e32 v12, v12
	v_exp_f32_e32 v10, v10
	s_mov_b32 s3, 0xc2ce8ed0
	v_cmp_ngt_f32_e32 vcc, s3, v11
	s_mov_b32 s3, 0x42b17218
	v_ldexp_f32 v10, v10, v12
	v_cndmask_b32_e32 v10, 0, v10, vcc
	v_cmp_nlt_f32_e32 vcc, s3, v11
	s_mov_b32 s3, 0x33800000
	s_nop 0
	v_cndmask_b32_e32 v10, v222, v10, vcc
	v_add_f32_e32 v14, 1.0, v10
	v_add_f32_e32 v12, -1.0, v14
	v_sub_f32_e32 v13, v12, v14
	v_add_f32_e32 v13, 1.0, v13
	v_sub_f32_e32 v12, v10, v12
	v_add_f32_e32 v15, v12, v13
	v_frexp_mant_f32_e32 v16, v14
	v_cvt_f64_f32_e32 v[12:13], v14
	v_frexp_exp_i32_f64_e32 v12, v[12:13]
	v_cmp_gt_f32_e32 vcc, s11, v16
	s_nop 1
	v_subbrev_co_u32_e32 v20, vcc, 0, v12, vcc
	v_sub_u32_e32 v12, 0, v20
	v_ldexp_f32 v13, v14, v12
	v_add_f32_e32 v14, -1.0, v13
	v_add_f32_e32 v16, 1.0, v13
	v_ldexp_f32 v12, v15, v12
	v_add_f32_e32 v15, 1.0, v14
	v_add_f32_e32 v17, -1.0, v16
	v_sub_f32_e32 v15, v13, v15
	v_sub_f32_e32 v13, v13, v17
	v_add_f32_e32 v15, v12, v15
	v_add_f32_e32 v12, v12, v13
	v_add_f32_e32 v21, v16, v12
	v_rcp_f32_e32 v23, v21
	v_sub_f32_e32 v13, v16, v21
	v_add_f32_e32 v22, v12, v13
	v_add_f32_e32 v13, v14, v15
	v_mul_f32_e32 v25, v13, v23
	v_sub_f32_e32 v12, v14, v13
	v_mul_f32_e32 v14, v21, v25
	v_fma_f32 v16, v25, v21, -v14
	v_fmac_f32_e32 v16, v25, v22
	v_add_f32_e32 v24, v15, v12
	v_add_f32_e32 v12, v14, v16
	v_sub_f32_e32 v15, v13, v12
	v_pk_add_f32 v[18:19], v[12:13], v[14:15] neg_lo:[0,1] neg_hi:[0,1]
	v_mov_b32_e32 v17, v12
	v_pk_add_f32 v[12:13], v[18:19], v[16:17] neg_lo:[0,1] neg_hi:[0,1]
	v_cmp_neq_f32_e32 vcc, s2, v10
	v_add_f32_e32 v13, v24, v13
	v_add_f32_e32 v12, v12, v13
	v_add_f32_e32 v13, v15, v12
	v_mul_f32_e32 v24, v23, v13
	v_mul_f32_e32 v14, v21, v24
	v_fma_f32 v16, v24, v21, -v14
	v_fmac_f32_e32 v16, v24, v22
	v_sub_f32_e32 v15, v15, v13
	v_add_f32_e32 v21, v12, v15
	v_add_f32_e32 v12, v14, v16
	v_sub_f32_e32 v15, v13, v12
	v_pk_add_f32 v[18:19], v[12:13], v[14:15] neg_lo:[0,1] neg_hi:[0,1]
	v_mov_b32_e32 v17, v12
	v_pk_add_f32 v[12:13], v[18:19], v[16:17] neg_lo:[0,1] neg_hi:[0,1]
	s_nop 0
	v_add_f32_e32 v13, v21, v13
	v_add_f32_e32 v12, v12, v13
	v_add_f32_e32 v13, v25, v24
	v_add_f32_e32 v12, v15, v12
	v_sub_f32_e32 v14, v13, v25
	v_mul_f32_e32 v12, v23, v12
	v_sub_f32_e32 v14, v24, v14
	v_add_f32_e32 v14, v14, v12
	v_add_f32_e32 v16, v13, v14
	v_mul_f32_e32 v17, v16, v16
	v_fmamk_f32 v12, v17, 0x3e9b6dac, v220
	v_fmaak_f32 v155, v17, v12, 0x3f2aaada
	v_cvt_f32_i32_e32 v12, v20
	v_sub_f32_e32 v13, v16, v13
	v_sub_f32_e32 v13, v14, v13
	v_ldexp_f32 v18, v13, 1
	v_mul_f32_e32 v13, v16, v17
	v_ldexp_f32 v15, v16, 1
	v_pk_mul_f32 v[16:17], v[12:13], v[154:155]
	s_nop 0
	v_fma_f32 v14, v12, s14, -v16
	v_fmac_f32_e32 v14, 0xb102e308, v12
	v_pk_add_f32 v[12:13], v[16:17], v[14:15]
	s_nop 0
	v_sub_f32_e32 v15, v13, v15
	v_sub_f32_e32 v15, v17, v15
	v_add_f32_e32 v19, v18, v15
	v_mov_b32_e32 v18, v16
	v_pk_add_f32 v[16:17], v[12:13], v[16:17] neg_lo:[0,1] neg_hi:[0,1]
	v_pk_add_f32 v[20:21], v[12:13], v[18:19]
	v_mov_b32_e32 v15, v12
	v_mov_b32_e32 v17, v21
	v_pk_add_f32 v[22:23], v[14:15], v[16:17] neg_lo:[0,1] neg_hi:[0,1]
	v_pk_add_f32 v[14:15], v[14:15], v[16:17]
	v_mov_b32_e32 v18, v19
	v_pk_add_f32 v[16:17], v[14:15], v[12:13] op_sel:[1,0] op_sel_hi:[0,1] neg_lo:[0,1] neg_hi:[0,1]
	v_pk_add_f32 v[24:25], v[20:21], v[16:17] op_sel_hi:[1,0] neg_lo:[0,1] neg_hi:[0,1]
	v_mov_b32_e32 v20, v21
	v_mov_b32_e32 v21, v15
	v_pk_mov_b32 v[16:17], v[12:13], v[16:17] op_sel:[1,0]
	v_mov_b32_e32 v19, v12
	v_pk_add_f32 v[16:17], v[20:21], v[16:17] neg_lo:[0,1] neg_hi:[0,1]
	v_mov_b32_e32 v24, v22
	v_pk_add_f32 v[12:13], v[18:19], v[16:17] neg_lo:[0,1] neg_hi:[0,1]
	v_mov_b32_e32 v23, v15
	v_pk_add_f32 v[16:17], v[24:25], v[12:13]
	s_nop 0
	v_pk_add_f32 v[18:19], v[16:17], v[16:17] op_sel:[0,1] op_sel_hi:[1,0]
	s_nop 0
	v_pk_add_f32 v[14:15], v[14:15], v[18:19] op_sel:[1,0] op_sel_hi:[0,1]
	v_mov_b32_e32 v17, v14
	v_pk_add_f32 v[20:21], v[16:17], v[22:23] neg_lo:[0,1] neg_hi:[0,1]
	v_mov_b32_e32 v13, v18
	v_sub_f32_e32 v15, v16, v20
	v_pk_add_f32 v[12:13], v[12:13], v[20:21] neg_lo:[0,1] neg_hi:[0,1]
	v_sub_f32_e32 v15, v22, v15
	v_add_f32_e32 v12, v12, v15
	v_add_f32_e32 v12, v12, v13
	v_add_f32_e32 v12, v14, v12
	v_cndmask_b32_e32 v12, v222, v12, vcc
	v_cmp_lt_f32_e64 vcc, |v10|, s3
	s_nop 1
	v_cndmask_b32_e32 v10, v12, v10, vcc
	v_sub_f32_e32 v10, v10, v11

; __device__ __forceinline__ float sigm(float x) { return __builtin_amdgcn_rcpf(1.f + __expf(-x)); }
; __device__ __forceinline__ void lru_pass(LAS unsigned char* L, int mode, const bf16_t* Z, const bf16_t* LWT, const float* conv_w, const float* conv_b, const float* b_a, const float* b_x, const float* lam,
;                          float* LSUM, const float* LCAR, bf16_t* Y) {
;     ...
;             for (int td = 0; td < 4; ++td) { const int d = td * 16 + fr, ch = n * 64 + d; const float lm = lam[g * 512 + ch]; const float sp = lm > 0.f ? log1pf(expf(-lm)) : -lm + log1pf(expf(lm));
;                 const float ba_ = b_a[g * 512 + ch], bx_ = b_x[g * 512 + ch];
; #pragma unroll
;                 for (int r = 0; r < 4; ++r) { const int i = ti * 16 + 4 * fq + r; const float la = -8.f * sigm(aa[td][r] + ba_) * sp;
;                     const float a_ = __expf(la), x2 = 2.f * la; const float om = (x2 > -0.02f) ? -x2 * (1.f + x2 * (0.5f + x2 * (1.f / 6.f))) : 1.f - a_ * a_;
;                     AA[g * 4160 + i * 65 + d] = a_; UU[g * 4160 + i * 65 + d] = __builtin_amdgcn_sqrtf(om) * sigm(ax[td][r] + bx_) * xc[i * 65 + d]; } } }
;         __syncthreads();
;         if (tid < 128) { const int g = tid >> 6, d = tid & 63, ch = n * 64 + d; const size_t ix = ((size_t)(b * 256 + seg) * 2 + g) * 512 + ch;
;             if (mode == 0) { float P = 1.f, E = 0.f;
;                 for (int st = 0; st < 64; ++st) { const int i = g ? 63 - st : st; const float a_ = AA[g * 4160 + i * 65 + d]; E = a_ * E + UU[g * 4160 + i * 65 + d]; P *= a_; }
;                 LSUM[2 * ix] = P; LSUM[2 * ix + 1] = E; }
;             else { float hc = LCAR[ix];
.LBB0_618:
	s_or_b64 exec, exec, s[20:21]
	v_lshlrev_b32_e32 v38, 2, v196
	v_add_u32_e32 v38, 0x21eb0, v38
	ds_write_b32 v38, v10 offset:18432
	s_branch .Llru_c3_c
.Llru_c3_b:
	v_lshlrev_b32_e32 v38, 2, v196
	v_add_u32_e32 v38, 0x21eb0, v38
	ds_read_b32 v10, v38 offset:18432
	ds_read_b32 v11, v38 offset:20480
	ds_read_b32 v14, v38 offset:22528
	s_waitcnt lgkmcnt(0)
.Llru_c3_c:
	s_cmp_lg_u32 s98, 0
	s_cbranch_scc1 .Llru_c3_d0
	global_load_dword v11, v[28:29], off offset:192
.Llru_c3_d0:
	s_cmp_lg_u32 s98, 0
	s_cbranch_scc1 .Llru_c3_d1
	global_load_dword v14, v[30:31], off offset:192
.Llru_c3_d1:
	s_mov_b32 s4, 0xc1000000
	s_mov_b32 s2, 0x3e2aaaab
	s_mov_b32 s3, 0xbca3d70a
	s_waitcnt vmcnt(1)
	v_add_f32_e32 v6, v6, v11
	v_mul_f32_e32 v6, 0xbfb8aa3b, v6
	v_exp_f32_e32 v6, v6
	s_waitcnt vmcnt(0)
	s_cmp_lg_u32 s98, 0
	s_cbranch_scc1 .Llru_c3_e
	v_lshlrev_b32_e32 v38, 2, v196
	v_add_u32_e32 v38, 0x21eb0, v38
	ds_write_b32 v38, v11 offset:20480
	ds_write_b32 v38, v14 offset:22528
.Llru_c3_e:
	v_add_f32_e32 v2, v2, v14
	v_mul_f32_e32 v2, 0xbfb8aa3b, v2
	v_exp_f32_e32 v2, v2
	v_add_f32_e32 v6, 1.0, v6
	v_rcp_f32_e32 v13, v6
	v_add_f32_e32 v6, v7, v11
	v_mul_f32_e32 v6, 0xbfb8aa3b, v6
	v_exp_f32_e32 v6, v6
	v_add_f32_e32 v2, 1.0, v2
	v_rcp_f32_e32 v2, v2
	v_add_f32_e32 v3, v3, v14
	v_add_f32_e32 v6, 1.0, v6
	v_rcp_f32_e32 v12, v6
	v_mul_f32_e32 v3, 0xbfb8aa3b, v3
	v_exp_f32_e32 v3, v3
	v_pk_mul_f32 v[6:7], v[12:13], s[4:5] op_sel_hi:[1,0]
	s_nop 0
	v_pk_mul_f32 v[6:7], v[10:11], v[6:7] op_sel_hi:[0,1]
	v_mul_f32_e32 v12, 0x3fb8aa3b, v7
	v_exp_f32_e32 v15, v12
	v_pk_add_f32 v[12:13], v[6:7], v[6:7]
	v_add_f32_e32 v3, 1.0, v3
	v_fma_f32 v7, v13, s2, 0.5
	v_fma_f32 v7, v13, v7, 1.0
	v_mul_f32_e64 v7, v7, -v13
	v_fma_f32 v16, -v15, v15, 1.0
	v_cmp_lt_f32_e64 s[44:45], s3, v13
	ds_write_b32 v68, v15 offset:62912
	v_cmp_lt_f32_e32 vcc, s3, v12
	v_cndmask_b32_e64 v7, v16, v7, s[44:45]
	v_sqrt_f32_e32 v7, v7
	v_rcp_f32_e32 v3, v3
	v_mul_f32_e32 v2, v2, v7
	ds_read_b32 v7, v69 offset:192
	s_waitcnt lgkmcnt(0)
	v_mul_f32_e32 v2, v7, v2
	ds_write_b32 v84, v2
	v_mul_f32_e32 v2, 0x3fb8aa3b, v6
	v_exp_f32_e32 v2, v2
	v_fma_f32 v6, v12, s2, 0.5
	v_fma_f32 v6, v12, v6, 1.0
	v_mul_f32_e64 v6, v6, -v12
	v_fma_f32 v7, -v2, v2, 1.0
	v_cndmask_b32_e32 v6, v7, v6, vcc
	ds_write_b32 v85, v2 offset:62980
	v_sqrt_f32_e32 v2, v6
	s_nop 0
	v_mul_f32_e32 v2, v3, v2
	ds_read_b32 v3, v69 offset:452
	s_waitcnt lgkmcnt(0)
	v_mul_f32_e32 v2, v3, v2
	ds_write_b32 v86, v2
	v_add_f32_e32 v2, v8, v11
	v_mul_f32_e32 v2, 0xbfb8aa3b, v2
	v_exp_f32_e32 v2, v2
	s_nop 0
	v_add_f32_e32 v2, 1.0, v2
	v_rcp_f32_e32 v3, v2
	v_add_f32_e32 v2, v4, v14
	v_mul_f32_e32 v2, 0xbfb8aa3b, v2
	v_exp_f32_e32 v2, v2
	s_nop 0
	v_add_f32_e32 v2, 1.0, v2
	v_rcp_f32_e32 v4, v2
	v_add_f32_e32 v2, v9, v11
	v_mul_f32_e32 v2, 0xbfb8aa3b, v2
	v_exp_f32_e32 v2, v2
	s_nop 0
	v_add_f32_e32 v2, 1.0, v2
	v_rcp_f32_e32 v2, v2
	s_nop 0
	v_pk_mul_f32 v[2:3], v[2:3], s[4:5] op_sel_hi:[1,0]
	s_nop 0
	v_pk_mul_f32 v[2:3], v[10:11], v[2:3] op_sel_hi:[0,1]
	v_mul_f32_e32 v6, 0x3fb8aa3b, v3
	v_exp_f32_e32 v8, v6
	v_pk_add_f32 v[6:7], v[2:3], v[2:3]
	v_mul_f32_e32 v2, 0x3fb8aa3b, v2
	v_fma_f32 v3, v7, s2, 0.5
	v_fma_f32 v3, v7, v3, 1.0
	v_mul_f32_e64 v3, v3, -v7
	v_fma_f32 v9, -v8, v8, 1.0
	v_cmp_lt_f32_e64 s[44:45], s3, v7
	ds_write_b32 v85, v8 offset:63240
	v_exp_f32_e32 v2, v2
	v_cndmask_b32_e64 v3, v9, v3, s[44:45]
	v_sqrt_f32_e32 v3, v3
	v_cmp_lt_f32_e32 vcc, s3, v6
	v_mul_f32_e32 v3, v4, v3
	ds_read_b32 v4, v69 offset:712
	s_waitcnt lgkmcnt(0)
	v_mul_f32_e32 v3, v4, v3
	ds_write_b32 v87, v3
	v_fma_f32 v3, v6, s2, 0.5
	v_fma_f32 v3, v6, v3, 1.0
	v_mul_f32_e64 v3, v3, -v6
	v_fma_f32 v4, -v2, v2, 1.0
	v_cndmask_b32_e32 v3, v4, v3, vcc
	ds_write_b32 v85, v2 offset:63500
	v_sqrt_f32_e32 v2, v3
	v_add_f32_e32 v3, v5, v14
	v_mul_f32_e32 v3, 0xbfb8aa3b, v3
	v_exp_f32_e32 v3, v3
	s_nop 0
	v_add_f32_e32 v3, 1.0, v3
	v_rcp_f32_e32 v3, v3
	s_nop 0
	v_mul_f32_e32 v2, v3, v2
	ds_read_b32 v3, v69 offset:972
	s_waitcnt lgkmcnt(0)
	v_mul_f32_e32 v2, v3, v2
	ds_write_b32 v88, v2
	s_waitcnt lgkmcnt(0)
	s_barrier
	s_and_saveexec_b64 s[20:21], s[42:43]
	s_cbranch_execz .LBB0_623
	s_lshl_b32 s4, s66, 8
	s_or_b32 s4, s4, s68
	s_ashr_i32 s5, s4, 31
	s_lshl_b64 s[4:5], s[4:5], 10
	v_lshl_add_u64 v[2:3], s[4:5], 0, v[198:199]
	v_lshl_add_u64 v[2:3], v[2:3], 0, v[48:49]
	s_andn2_b64 vcc, exec, s[62:63]
	s_mov_b64 s[22:23], -1
	s_cbranch_vccnz .LBB0_621
; __device__ __forceinline__ void lru_pass(LAS unsigned char* L, int mode, const bf16_t* Z, const bf16_t* LWT, const float* conv_w, const float* conv_b, const float* b_a, const float* b_x, const float* lam,
;                          float* LSUM, const float* LCAR, bf16_t* Y) {
;     ...
;         if (tid < 128) { const int g = tid >> 6, d = tid & 63, ch = n * 64 + d; const size_t ix = ((size_t)(b * 256 + seg) * 2 + g) * 512 + ch;
;             if (mode == 0) { float P = 1.f, E = 0.f;
;                 for (int st = 0; st < 64; ++st) { const int i = g ? 63 - st : st; const float a_ = AA[g * 4160 + i * 65 + d]; E = a_ * E + UU[g * 4160 + i * 65 + d]; P *= a_; }
;                 LSUM[2 * ix] = P; LSUM[2 * ix + 1] = E; }
	ds_read_b32 v5, v95 offset:62720
	ds_read_b32 v6, v56
	ds_read_b32 v7, v202 offset:62720
	ds_read_b32 v8, v201
	ds_read_b32 v4, v96 offset:62720
	ds_read_b32 v9, v89
	ds_read_b32 v50, v249 offset:62720
	ds_read_b32 v10, v250
	s_waitcnt lgkmcnt(6)
	v_fmac_f32_e32 v6, 0, v5
	s_waitcnt lgkmcnt(4)
	v_fmac_f32_e32 v8, v6, v7
	v_mul_f32_e32 v52, v5, v7
	s_waitcnt lgkmcnt(2)
	v_fmac_f32_e32 v9, v8, v4
	ds_read_b32 v6, v203 offset:62720
	ds_read_b32 v5, v98
	ds_read_b32 v206, v99 offset:62720
	ds_read_b32 v7, v100
	ds_read_b32 v8, v101 offset:62720
	ds_read_b32 v11, v102
	ds_read_b32 v208, v103 offset:62720
	ds_read_b32 v13, v104
	s_waitcnt lgkmcnt(8)
	v_fmac_f32_e32 v10, v9, v50
	s_waitcnt lgkmcnt(6)
	v_fmac_f32_e32 v5, v10, v6
	s_waitcnt lgkmcnt(4)
	v_fmac_f32_e32 v7, v5, v206
	s_waitcnt lgkmcnt(2)
	v_fmac_f32_e32 v11, v7, v8
	ds_read_b32 v12, v105 offset:62720
	ds_read_b32 v5, v106
	ds_read_b32 v210, v107 offset:62720
	ds_read_b32 v7, v108
	ds_read_b32 v16, v109 offset:62720
	ds_read_b32 v9, v110
	ds_read_b32 v212, v111 offset:62720
	ds_read_b32 v10, v112
	s_waitcnt lgkmcnt(8)
	v_fmac_f32_e32 v13, v11, v208
	s_waitcnt lgkmcnt(6)
	v_fmac_f32_e32 v5, v13, v12
	s_waitcnt lgkmcnt(4)
	v_fmac_f32_e32 v7, v5, v210
	s_waitcnt lgkmcnt(2)
	v_fmac_f32_e32 v9, v7, v16
	ds_read_b32 v22, v113 offset:62720
	ds_read_b32 v5, v114
	ds_read_b32 v214, v115 offset:62720
	ds_read_b32 v7, v116
	ds_read_b32 v26, v117 offset:62720
	ds_read_b32 v11, v118
	ds_read_b32 v216, v119 offset:62720
	ds_read_b32 v13, v120
	s_waitcnt lgkmcnt(8)
	v_fmac_f32_e32 v10, v9, v212
	s_waitcnt lgkmcnt(6)
	v_fmac_f32_e32 v5, v10, v22
	s_waitcnt lgkmcnt(4)
	v_fmac_f32_e32 v7, v5, v214
	s_waitcnt lgkmcnt(2)
	v_fmac_f32_e32 v11, v7, v26
	ds_read_b32 v30, v121 offset:62720
	ds_read_b32 v5, v122
	ds_read_b32 v218, v123 offset:62720
	ds_read_b32 v7, v124
	ds_read_b32 v10, v125 offset:62720
	ds_read_b32 v9, v126
	s_waitcnt lgkmcnt(6)
	v_fmac_f32_e32 v13, v11, v216
	v_mov_b32_e32 v21, v220
	ds_read_b32 v220, v127 offset:62720
	ds_read_b32 v11, v128
	s_waitcnt lgkmcnt(6)
	v_fmac_f32_e32 v5, v13, v30
	s_waitcnt lgkmcnt(4)
	v_fmac_f32_e32 v7, v5, v218
	s_waitcnt lgkmcnt(2)
	v_fmac_f32_e32 v9, v7, v10
	ds_read_b32 v14, v129 offset:62720
	ds_read_b32 v5, v130
	ds_read_b32 v204, v131 offset:62720
	ds_read_b32 v7, v132
	ds_read_b32 v18, v133 offset:62720
	ds_read_b32 v13, v134
	s_waitcnt lgkmcnt(6)
	v_fmac_f32_e32 v11, v9, v220
	v_mov_b32_e32 v45, v94
	v_mov_b32_e32 v47, v95
	v_mov_b64_e32 v[94:95], v[92:93]
	v_mov_b64_e32 v[92:93], v[198:199]
	ds_read_b32 v198, v135 offset:62720
	ds_read_b32 v15, v136
	s_waitcnt lgkmcnt(6)
	v_fmac_f32_e32 v5, v11, v14
	s_waitcnt lgkmcnt(4)
	v_fmac_f32_e32 v7, v5, v204
	ds_read_b32 v20, v137 offset:62720
	ds_read_b32 v5, v138
	s_waitcnt lgkmcnt(4)
	v_fmac_f32_e32 v13, v7, v18
	v_mov_b32_e32 v54, v202
	ds_read_b32 v202, v139 offset:62720
	ds_read_b32 v7, v140
	ds_read_b32 v24, v141 offset:62720
	ds_read_b32 v9, v142
	ds_read_b32 v36, v143 offset:62720
	ds_read_b32 v11, v144
	s_waitcnt lgkmcnt(8)
	v_fmac_f32_e32 v15, v13, v198
	s_waitcnt lgkmcnt(6)
	v_fmac_f32_e32 v5, v15, v20
	s_waitcnt lgkmcnt(4)
	v_fmac_f32_e32 v7, v5, v202
	s_waitcnt lgkmcnt(2)
	v_fmac_f32_e32 v9, v7, v24
	ds_read_b32 v28, v145 offset:62720
	ds_read_b32 v5, v146
	ds_read_b32 v42, v147 offset:62720
	ds_read_b32 v7, v148
	ds_read_b32 v32, v149 offset:62720
	ds_read_b32 v13, v150
	ds_read_b32 v38, v151 offset:62720
	ds_read_b32 v15, v152
	s_waitcnt lgkmcnt(8)
	v_fmac_f32_e32 v11, v9, v36
	s_waitcnt lgkmcnt(6)
	v_fmac_f32_e32 v5, v11, v28
	s_waitcnt lgkmcnt(4)
	v_fmac_f32_e32 v7, v5, v42
	s_waitcnt lgkmcnt(2)
	v_fmac_f32_e32 v13, v7, v32
	s_waitcnt lgkmcnt(0)
	v_fmac_f32_e32 v15, v13, v38
	ds_read_b32 v48, v153 offset:62720
	ds_read_b32 v53, v156
	ds_read_b32 v5, v157 offset:62720
	ds_read_b32 v51, v158
	ds_read_b32 v7, v159 offset:62720
	ds_read_b32 v207, v160
	ds_read_b32 v9, v161 offset:62720
	ds_read_b32 v209, v162
	s_waitcnt lgkmcnt(6)
	v_fmac_f32_e32 v53, v15, v48
	v_mul_f32_e32 v11, v52, v4
	v_mov_b32_e32 v155, v96
	v_mov_b64_e32 v[96:97], v[90:91]
	v_mul_f32_e32 v90, v11, v50
	s_waitcnt lgkmcnt(4)
	v_pk_fma_f32 v[50:51], v[52:53], v[4:5], v[50:51]
	ds_read_b32 v13, v163 offset:62720
	ds_read_b32 v211, v164
	ds_read_b32 v17, v165 offset:62720
	ds_read_b32 v213, v166
	ds_read_b32 v23, v167 offset:62720
	ds_read_b32 v215, v168
	ds_read_b32 v27, v169 offset:62720
	ds_read_b32 v217, v170
	v_mov_b32_e32 v91, v51
	s_waitcnt lgkmcnt(11)
	v_pk_mul_f32 v[50:51], v[90:91], v[6:7]
	s_waitcnt lgkmcnt(10)
	v_pk_fma_f32 v[52:53], v[90:91], v[6:7], v[206:207]
	v_pk_mul_f32 v[50:51], v[50:51], v[206:207]
	ds_read_b32 v31, v171 offset:62720
	ds_read_b32 v219, v172
	ds_read_b32 v11, v173 offset:62720
	ds_read_b32 v221, v174
	ds_read_b32 v15, v175 offset:62720
	ds_read_b32 v205, v176
	ds_read_b32 v19, v177 offset:62720
	ds_read_b32 v199, v178
	v_mov_b32_e32 v52, v50
	s_waitcnt lgkmcnt(14)
	v_pk_mul_f32 v[50:51], v[50:51], v[8:9]
	v_pk_fma_f32 v[52:53], v[52:53], v[8:9], v[208:209]
	v_pk_mul_f32 v[50:51], v[50:51], v[208:209]
	v_mov_b32_e32 v4, v5
	v_mov_b32_e32 v51, v53
	v_pk_mul_f32 v[52:53], v[50:51], v[12:13]
	v_pk_fma_f32 v[50:51], v[50:51], v[12:13], v[210:211]
	v_pk_mul_f32 v[52:53], v[52:53], v[210:211]
	v_mov_b32_e32 v6, v7
	v_mov_b32_e32 v50, v52
	s_waitcnt lgkmcnt(13)
	v_pk_mul_f32 v[52:53], v[52:53], v[16:17]
	s_waitcnt lgkmcnt(12)
	v_pk_fma_f32 v[50:51], v[50:51], v[16:17], v[212:213]
	v_pk_mul_f32 v[52:53], v[52:53], v[212:213]
	v_mov_b32_e32 v8, v17
	v_mov_b32_e32 v53, v51
	s_waitcnt lgkmcnt(11)
	v_pk_mul_f32 v[50:51], v[52:53], v[22:23]
	s_waitcnt lgkmcnt(10)
; __device__ __forceinline__ void lru_pass(LAS unsigned char* L, int mode, const bf16_t* Z, const bf16_t* LWT, const float* conv_w, const float* conv_b, const float* b_a, const float* b_x, const float* lam,
;                          float* LSUM, const float* LCAR, bf16_t* Y) {
;     ...
;             if (mode == 0) { float P = 1.f, E = 0.f;
;                 for (int st = 0; st < 64; ++st) { const int i = g ? 63 - st : st; const float a_ = AA[g * 4160 + i * 65 + d]; E = a_ * E + UU[g * 4160 + i * 65 + d]; P *= a_; }
;                 LSUM[2 * ix] = P; LSUM[2 * ix + 1] = E; }
	v_pk_fma_f32 v[52:53], v[52:53], v[22:23], v[214:215]
	v_pk_mul_f32 v[50:51], v[50:51], v[214:215]
	v_mov_b32_e32 v90, v17
	v_mov_b32_e32 v52, v50
	s_waitcnt lgkmcnt(9)
	v_pk_mul_f32 v[50:51], v[50:51], v[26:27]
	s_waitcnt lgkmcnt(8)
	v_pk_fma_f32 v[52:53], v[52:53], v[26:27], v[216:217]
	v_pk_mul_f32 v[50:51], v[50:51], v[216:217]
	s_waitcnt lgkmcnt(3)
	v_mov_b32_e32 v12, v15
	v_mov_b32_e32 v51, v53
	v_pk_mul_f32 v[52:53], v[50:51], v[30:31]
	v_pk_fma_f32 v[50:51], v[50:51], v[30:31], v[218:219]
	v_pk_mul_f32 v[52:53], v[52:53], v[218:219]
	s_waitcnt lgkmcnt(1)
	v_mov_b32_e32 v16, v19
	v_mov_b32_e32 v50, v52
	v_pk_mul_f32 v[52:53], v[52:53], v[10:11]
	v_pk_fma_f32 v[50:51], v[50:51], v[10:11], v[220:221]
	v_pk_mul_f32 v[52:53], v[52:53], v[220:221]
	v_mov_b32_e32 v220, v21
	v_mov_b32_e32 v53, v51
	v_pk_mul_f32 v[50:51], v[52:53], v[14:15]
	ds_read_b32 v21, v179 offset:62720
	v_pk_mul_f32 v[50:51], v[50:51], v[204:205]
	v_pk_fma_f32 v[52:53], v[52:53], v[14:15], v[204:205]
	v_mov_b32_e32 v10, v203
	v_mov_b32_e32 v52, v50
	v_pk_mul_f32 v[50:51], v[50:51], v[18:19]
	s_waitcnt lgkmcnt(1)
	v_pk_fma_f32 v[52:53], v[52:53], v[18:19], v[198:199]
	v_pk_mul_f32 v[50:51], v[50:51], v[198:199]
	ds_read_b32 v203, v180
	ds_read_b32 v25, v181 offset:62720
	ds_read_b32 v37, v182
	ds_read_b32 v29, v183 offset:62720
	ds_read_b32 v43, v184
	ds_read_b32 v33, v185 offset:62720
	ds_read_b32 v39, v186
	v_mov_b32_e32 v51, v53
	s_waitcnt lgkmcnt(7)
	v_pk_mul_f32 v[52:53], v[50:51], v[20:21]
	s_waitcnt lgkmcnt(6)
	v_pk_fma_f32 v[50:51], v[50:51], v[20:21], v[202:203]
	v_pk_mul_f32 v[52:53], v[52:53], v[202:203]
	v_mov_b32_e32 v198, v23
	v_mov_b32_e32 v50, v52
	s_waitcnt lgkmcnt(5)
	v_pk_mul_f32 v[52:53], v[52:53], v[24:25]
	v_mov_b32_e32 v202, v27
	s_waitcnt lgkmcnt(4)
	v_pk_mul_f32 v[52:53], v[52:53], v[36:37]
	v_pk_fma_f32 v[36:37], v[50:51], v[24:25], v[36:37]
	v_mov_b32_e32 v50, v9
	v_mov_b32_e32 v53, v37
	s_waitcnt lgkmcnt(3)
	v_pk_mul_f32 v[36:37], v[52:53], v[28:29]
	v_mov_b32_e32 v22, v21
	s_waitcnt lgkmcnt(2)
	v_pk_mul_f32 v[36:37], v[36:37], v[42:43]
	v_pk_fma_f32 v[42:43], v[52:53], v[28:29], v[42:43]
	v_mov_b32_e32 v52, v13
	v_mov_b32_e32 v42, v36
	s_waitcnt lgkmcnt(1)
	v_pk_mul_f32 v[36:37], v[36:37], v[32:33]
	v_mov_b32_e32 v26, v25
	s_waitcnt lgkmcnt(0)
	v_pk_mul_f32 v[36:37], v[36:37], v[38:39]
	v_pk_fma_f32 v[38:39], v[42:43], v[32:33], v[38:39]
	v_mov_b32_e32 v42, v7
	v_mov_b32_e32 v37, v39
	ds_read_b32 v49, v187 offset:62720
	ds_read_b32 v39, v188
	ds_read_b32 v43, v189 offset:62720
	ds_read_b32 v51, v190
	ds_read_b32 v53, v191 offset:62720
	ds_read_b32 v91, v192
	ds_read_b32 v199, v193 offset:62720
	ds_read_b32 v203, v194
	s_waitcnt lgkmcnt(7)
	v_pk_mul_f32 v[204:205], v[36:37], v[48:49]
	v_mov_b32_e32 v38, v5
	v_pk_mul_f32 v[4:5], v[204:205], v[4:5]
	s_waitcnt lgkmcnt(6)
	v_pk_fma_f32 v[36:37], v[36:37], v[48:49], v[38:39]
	v_mov_b32_e32 v30, v29
	v_mov_b32_e32 v36, v4
	v_pk_mul_f32 v[4:5], v[4:5], v[6:7]
	v_mov_b32_e32 v6, v9
	v_pk_mul_f32 v[4:5], v[4:5], v[6:7]
	s_waitcnt lgkmcnt(4)
	v_pk_fma_f32 v[6:7], v[36:37], v[42:43], v[50:51]
	v_mov_b32_e32 v36, v33
	v_mov_b32_e32 v5, v7
	s_waitcnt lgkmcnt(3)
	v_pk_mul_f32 v[6:7], v[4:5], v[52:53]
	s_waitcnt lgkmcnt(2)
	v_pk_fma_f32 v[4:5], v[4:5], v[52:53], v[90:91]
	v_pk_mul_f32 v[6:7], v[6:7], v[8:9]
	v_mov_b32_e32 v8, v23
	v_mov_b32_e32 v4, v6
	v_pk_mul_f32 v[6:7], v[6:7], v[8:9]
	v_mov_b32_e32 v8, v27
	v_pk_mul_f32 v[6:7], v[6:7], v[8:9]
	s_waitcnt lgkmcnt(0)
	v_pk_fma_f32 v[4:5], v[4:5], v[198:199], v[202:203]
	v_mov_b32_e32 v203, v10
	v_mov_b32_e32 v7, v5
	v_mov_b32_e32 v4, v31
	ds_read_b32 v5, v195 offset:62720
	ds_read_b32 v9, v223
	ds_read_b32 v13, v224 offset:62720
	ds_read_b32 v17, v225
	ds_read_b32 v23, v226 offset:62720
	ds_read_b32 v27, v227
	ds_read_b32 v31, v228 offset:62720
	ds_read_b32 v37, v229
	s_waitcnt lgkmcnt(7)
; __device__ __forceinline__ void lru_pass(LAS unsigned char* L, int mode, const bf16_t* Z, const bf16_t* LWT, const float* conv_w, const float* conv_b, const float* b_a, const float* b_x, const float* lam,
;                          float* LSUM, const float* LCAR, bf16_t* Y) {
;     ...
;             if (mode == 0) { float P = 1.f, E = 0.f;
;                 for (int st = 0; st < 64; ++st) { const int i = g ? 63 - st : st; const float a_ = AA[g * 4160 + i * 65 + d]; E = a_ * E + UU[g * 4160 + i * 65 + d]; P *= a_; }
;                 LSUM[2 * ix] = P; LSUM[2 * ix + 1] = E; }
	v_pk_mul_f32 v[38:39], v[6:7], v[4:5]
	v_mov_b32_e32 v10, v11
	v_mov_b32_e32 v8, v11
	v_pk_mul_f32 v[10:11], v[38:39], v[10:11]
	s_waitcnt lgkmcnt(6)
	v_pk_fma_f32 v[6:7], v[6:7], v[4:5], v[8:9]
	v_mov_b32_e32 v4, v15
	v_mov_b32_e32 v6, v10
	v_pk_mul_f32 v[8:9], v[10:11], v[4:5]
	v_mov_b32_e32 v4, v19
	v_pk_mul_f32 v[8:9], v[8:9], v[4:5]
	s_waitcnt lgkmcnt(4)
	v_pk_fma_f32 v[6:7], v[6:7], v[12:13], v[16:17]
	v_mov_b32_e32 v4, v25
	v_mov_b32_e32 v9, v7
	s_waitcnt lgkmcnt(3)
	v_pk_mul_f32 v[6:7], v[8:9], v[22:23]
	s_waitcnt lgkmcnt(2)
	v_pk_fma_f32 v[8:9], v[8:9], v[22:23], v[26:27]
	v_pk_mul_f32 v[6:7], v[6:7], v[4:5]
	v_mov_b32_e32 v4, v29
	v_mov_b32_e32 v8, v6
	v_pk_mul_f32 v[6:7], v[6:7], v[4:5]
	v_mov_b32_e32 v4, v33
	v_pk_mul_f32 v[6:7], v[6:7], v[4:5]
	s_waitcnt lgkmcnt(0)
	v_pk_fma_f32 v[8:9], v[8:9], v[30:31], v[36:37]
	v_mov_b32_e32 v4, v43
	v_mov_b32_e32 v7, v9
	v_mov_b32_e32 v8, v49
	ds_read_b32 v9, v230 offset:62720
	ds_read_b32 v11, v231
	ds_read_b32 v15, v232 offset:62720
	ds_read_b32 v17, v233
	ds_read_b32 v19, v234 offset:62720
	ds_read_b32 v21, v235
	ds_read_b32 v25, v236 offset:62720
	ds_read_b32 v27, v237
	s_waitcnt lgkmcnt(7)
	v_pk_mul_f32 v[28:29], v[6:7], v[8:9]
	v_mov_b32_e32 v10, v43
	v_pk_mul_f32 v[28:29], v[28:29], v[4:5]
	s_waitcnt lgkmcnt(6)
	v_pk_fma_f32 v[6:7], v[6:7], v[8:9], v[10:11]
	v_mov_b32_e32 v4, v53
	v_mov_b32_e32 v6, v28
	v_mov_b32_e32 v14, v53
	v_pk_mul_f32 v[10:11], v[28:29], v[4:5]
	v_mov_b32_e32 v4, v199
	v_mov_b32_e32 v16, v199
	v_pk_mul_f32 v[10:11], v[10:11], v[4:5]
	s_waitcnt lgkmcnt(4)
	v_pk_fma_f32 v[6:7], v[6:7], v[14:15], v[16:17]
	v_mov_b32_e32 v18, v5
	v_mov_b32_e32 v11, v7
	s_waitcnt lgkmcnt(3)
	v_pk_mul_f32 v[4:5], v[10:11], v[18:19]
	v_mov_b32_e32 v6, v13
	v_mov_b32_e32 v20, v13
	v_pk_mul_f32 v[4:5], v[4:5], v[6:7]
	s_waitcnt lgkmcnt(2)
	v_pk_fma_f32 v[6:7], v[10:11], v[18:19], v[20:21]
	v_mov_b32_e32 v8, v23
	v_mov_b32_e32 v6, v4
	v_mov_b32_e32 v24, v23
	v_pk_mul_f32 v[4:5], v[4:5], v[8:9]
	v_mov_b32_e32 v8, v31
	v_mov_b32_e32 v26, v31
	v_pk_mul_f32 v[4:5], v[4:5], v[8:9]
	s_waitcnt lgkmcnt(0)
	v_pk_fma_f32 v[6:7], v[6:7], v[24:25], v[26:27]
	v_mov_b32_e32 v10, v9
	v_mov_b32_e32 v5, v7
	ds_read_b32 v11, v238 offset:62720
	ds_read_b32 v13, v239
	ds_read_b32 v17, v240 offset:62720
	ds_read_b32 v21, v241
	ds_read_b32 v29, v243 offset:62720
	ds_read_b32 v33, v244
	ds_read_b32 v37, v246 offset:62720
	ds_read_b32 v39, v247
	s_waitcnt lgkmcnt(7)
	v_pk_mul_f32 v[6:7], v[4:5], v[10:11]
	v_mov_b32_e32 v8, v15
	v_mov_b32_e32 v12, v15
	v_pk_mul_f32 v[6:7], v[6:7], v[8:9]
	s_waitcnt lgkmcnt(6)
	v_pk_fma_f32 v[4:5], v[4:5], v[10:11], v[12:13]
	v_mov_b32_e32 v8, v19
	v_mov_b32_e32 v4, v6
	v_mov_b32_e32 v16, v19
	v_pk_mul_f32 v[6:7], v[6:7], v[8:9]
	v_mov_b32_e32 v8, v25
	v_mov_b32_e32 v20, v25
	v_pk_mul_f32 v[6:7], v[6:7], v[8:9]
	s_waitcnt lgkmcnt(4)
	v_pk_fma_f32 v[4:5], v[4:5], v[16:17], v[20:21]
	v_mov_b32_e32 v28, v11
	v_mov_b32_e32 v7, v5
	s_waitcnt lgkmcnt(3)
	v_pk_mul_f32 v[4:5], v[6:7], v[28:29]
	v_mov_b32_e32 v8, v17
	v_mov_b32_e32 v32, v17
	v_pk_mul_f32 v[4:5], v[4:5], v[8:9]
	s_waitcnt lgkmcnt(2)
	v_pk_fma_f32 v[6:7], v[6:7], v[28:29], v[32:33]
	v_mov_b32_e32 v8, v29
	v_mov_b32_e32 v6, v4
	v_mov_b32_e32 v36, v29
	v_pk_mul_f32 v[4:5], v[4:5], v[8:9]
	s_waitcnt lgkmcnt(1)
	v_mov_b32_e32 v8, v37
	v_mov_b32_e32 v38, v37
	v_pk_mul_f32 v[4:5], v[4:5], v[8:9]
	s_waitcnt lgkmcnt(0)
	v_pk_fma_f32 v[6:7], v[6:7], v[36:37], v[38:39]
	v_mov_b64_e32 v[90:91], v[96:97]
	v_mov_b32_e32 v96, v155
	v_mov_b32_e32 v202, v54
	v_mov_b64_e32 v[198:199], v[92:93]
	v_mov_b64_e32 v[92:93], v[94:95]
	v_mov_b32_e32 v95, v47
	v_mov_b32_e32 v94, v45
	v_lshl_add_u64 v[42:43], v[2:3], 3, s[30:31]
	v_mov_b32_e32 v5, v7
	s_mov_b64 s[22:23], 0
	global_store_dwordx2 v[42:43], v[4:5], off
